# attention: merged descending lgkmcnt waits in MFMA runs; mlp_in epilogue: fmaxf canonicalisation folded into max(0,x) (128 fewer VALU per tile)
# speedup vs baseline: 1.0057x; 1.0041x over previous
; __device__ __forceinline__ unsigned cvt_pk_bf16(float lo, float hi) { const f32x2 v = (f32x2){lo, hi}; return __builtin_bit_cast(unsigned, __builtin_convertvector(v, bf16v2)); }
;     __device__ __forceinline__ void operator()(f32x4 (&acc)[2][2][4][2], const Unit& u, int wr, int wc, int fr, int fq, LAS unsigned char* xl, int wid, int lane) const {
;     ...
;         for (int ai = 0; ai < 2; ++ai)
; #pragma unroll
;             for (int m = 0; m < 4; ++m) { bf16_t* rowp = base + (size_t)(row0 + ai * HALF + m * 16) * ldc + col0;
; #pragma unroll
;                 for (int bj = 0; bj < 2; ++bj) { f32x4 v0 = acc[ai][bj][m][0], v1 = acc[ai][bj][m][1];
;                     if (MODE == 2) {
; #pragma unroll
;                         for (int e = 0; e < 4; ++e) { const float a = fmaxf(v0[e], 0.f), b = fmaxf(v1[e], 0.f); v0[e] = a * a; v1[e] = b * b; } }
;                     u32x4 w; w.x = cvt_pk_bf16(v0[0], v0[1]); w.y = cvt_pk_bf16(v0[2], v0[3]); w.z = cvt_pk_bf16(v1[0], v1[1]); w.w = cvt_pk_bf16(v1[2], v1[3]);
;                     *(u32x4*)(rowp + bj * HALF) = w; } }
.LBB0_186:
	v_max_f32_e32 v120, 0, v120
	v_max_f32_e32 v121, 0, v121
	v_pk_mul_f32 v[148:149], v[120:121], v[120:121]
	v_lshl_add_u32 v144, s20, 8, v140
	v_lshl_or_b32 v138, s69, 8, v142
	v_max_f32_e32 v122, 0, v122
	v_ashrrev_i32_e32 v139, 31, v138
	v_ashrrev_i32_e32 v145, 31, v144
	v_max_f32_e32 v124, 0, v124
	v_max_f32_e32 v125, 0, v125
	v_max_f32_e32 v120, 0, v126
	v_max_f32_e32 v121, 0, v127
	v_max_f32_e32 v123, 0, v123
	v_lshl_add_u64 v[146:147], v[138:139], 1, s[8:9]
	v_lshlrev_b64 v[138:139], 13, v[144:145]
	v_pk_mul_f32 v[124:125], v[124:125], v[124:125]
	v_pk_mul_f32 v[126:127], v[120:121], v[120:121]
	v_pk_mul_f32 v[150:151], v[122:123], v[122:123]
	v_lshl_add_u64 v[138:139], v[146:147], 0, v[138:139]
	v_cvt_pk_bf16_f32 v120, v124, v125
	v_cvt_pk_bf16_f32 v121, v126, v127
	v_cvt_pk_bf16_f32 v122, v148, v149
	v_cvt_pk_bf16_f32 v123, v150, v151
	v_max_f32_e32 v112, 0, v112
	v_max_f32_e32 v113, 0, v113
	global_store_dwordx4 v[138:139], v[120:123], off
	s_nop 1
	v_pk_mul_f32 v[120:121], v[112:113], v[112:113]
	v_max_f32_e32 v114, 0, v114
	v_max_f32_e32 v116, 0, v116
	v_max_f32_e32 v117, 0, v117
	v_max_f32_e32 v112, 0, v118
	v_max_f32_e32 v113, 0, v119
	v_max_f32_e32 v115, 0, v115
	v_pk_mul_f32 v[116:117], v[116:117], v[116:117]
	v_pk_mul_f32 v[118:119], v[112:113], v[112:113]
	v_pk_mul_f32 v[122:123], v[114:115], v[114:115]
	v_cvt_pk_bf16_f32 v112, v116, v117
	v_cvt_pk_bf16_f32 v113, v118, v119
	v_cvt_pk_bf16_f32 v114, v120, v121
	v_cvt_pk_bf16_f32 v115, v122, v123
	v_max_f32_e32 v104, 0, v104
	v_max_f32_e32 v105, 0, v105
	global_store_dwordx4 v[138:139], v[112:115], off offset:256
	s_nop 1
	v_pk_mul_f32 v[114:115], v[104:105], v[104:105]
	v_or_b32_e32 v112, 16, v144
	v_max_f32_e32 v106, 0, v106
	v_ashrrev_i32_e32 v113, 31, v112
	v_max_f32_e32 v108, 0, v108
	v_max_f32_e32 v109, 0, v109
	v_max_f32_e32 v104, 0, v110
	v_max_f32_e32 v105, 0, v111
	v_max_f32_e32 v107, 0, v107
	v_lshlrev_b64 v[112:113], 13, v[112:113]
	v_pk_mul_f32 v[108:109], v[108:109], v[108:109]
	v_pk_mul_f32 v[110:111], v[104:105], v[104:105]
	v_pk_mul_f32 v[116:117], v[106:107], v[106:107]
	v_lshl_add_u64 v[112:113], v[146:147], 0, v[112:113]
	v_cvt_pk_bf16_f32 v104, v108, v109
	v_cvt_pk_bf16_f32 v105, v110, v111
	v_cvt_pk_bf16_f32 v106, v114, v115
	v_cvt_pk_bf16_f32 v107, v116, v117
	v_max_f32_e32 v96, 0, v96
	v_max_f32_e32 v97, 0, v97
	global_store_dwordx4 v[112:113], v[104:107], off
	s_nop 1
	v_pk_mul_f32 v[104:105], v[96:97], v[96:97]
	v_max_f32_e32 v98, 0, v98
	v_max_f32_e32 v100, 0, v100
	v_max_f32_e32 v101, 0, v101
	v_max_f32_e32 v96, 0, v102
	v_max_f32_e32 v97, 0, v103
	v_max_f32_e32 v99, 0, v99
	v_pk_mul_f32 v[100:101], v[100:101], v[100:101]
	v_pk_mul_f32 v[102:103], v[96:97], v[96:97]
	v_pk_mul_f32 v[106:107], v[98:99], v[98:99]
	v_cvt_pk_bf16_f32 v96, v100, v101
	v_cvt_pk_bf16_f32 v97, v102, v103
	v_cvt_pk_bf16_f32 v98, v104, v105
	v_cvt_pk_bf16_f32 v99, v106, v107
	v_max_f32_e32 v88, 0, v88
	v_max_f32_e32 v89, 0, v89
	global_store_dwordx4 v[112:113], v[96:99], off offset:256
	s_nop 1
	v_pk_mul_f32 v[98:99], v[88:89], v[88:89]
	v_or_b32_e32 v96, 32, v144
	v_max_f32_e32 v90, 0, v90
	v_ashrrev_i32_e32 v97, 31, v96
	v_max_f32_e32 v92, 0, v92
	v_max_f32_e32 v93, 0, v93
	v_max_f32_e32 v88, 0, v94
	v_max_f32_e32 v89, 0, v95
	v_max_f32_e32 v91, 0, v91
	v_lshlrev_b64 v[96:97], 13, v[96:97]
	v_pk_mul_f32 v[92:93], v[92:93], v[92:93]
	v_pk_mul_f32 v[94:95], v[88:89], v[88:89]
	v_pk_mul_f32 v[100:101], v[90:91], v[90:91]
	v_lshl_add_u64 v[96:97], v[146:147], 0, v[96:97]
	v_cvt_pk_bf16_f32 v88, v92, v93
	v_cvt_pk_bf16_f32 v89, v94, v95
	v_cvt_pk_bf16_f32 v90, v98, v99
	v_cvt_pk_bf16_f32 v91, v100, v101
	v_max_f32_e32 v80, 0, v80
	v_max_f32_e32 v81, 0, v81
	global_store_dwordx4 v[96:97], v[88:91], off
	s_nop 1
	v_pk_mul_f32 v[88:89], v[80:81], v[80:81]
	v_max_f32_e32 v82, 0, v82
	v_max_f32_e32 v84, 0, v84
	v_max_f32_e32 v85, 0, v85
	v_max_f32_e32 v80, 0, v86
	v_max_f32_e32 v81, 0, v87
	v_max_f32_e32 v83, 0, v83
	v_pk_mul_f32 v[84:85], v[84:85], v[84:85]
	v_pk_mul_f32 v[86:87], v[80:81], v[80:81]
	v_pk_mul_f32 v[90:91], v[82:83], v[82:83]
	v_cvt_pk_bf16_f32 v80, v84, v85
	v_cvt_pk_bf16_f32 v81, v86, v87
	v_cvt_pk_bf16_f32 v82, v88, v89
	v_cvt_pk_bf16_f32 v83, v90, v91
	v_max_f32_e32 v72, 0, v72
	v_max_f32_e32 v73, 0, v73
	global_store_dwordx4 v[96:97], v[80:83], off offset:256
	s_nop 1
	v_pk_mul_f32 v[82:83], v[72:73], v[72:73]
	v_or_b32_e32 v80, 48, v144
	v_max_f32_e32 v74, 0, v74
	v_ashrrev_i32_e32 v81, 31, v80
	v_max_f32_e32 v76, 0, v76
	v_max_f32_e32 v77, 0, v77
	v_max_f32_e32 v72, 0, v78
	v_max_f32_e32 v73, 0, v79
	v_max_f32_e32 v75, 0, v75
	v_lshlrev_b64 v[80:81], 13, v[80:81]
	v_pk_mul_f32 v[76:77], v[76:77], v[76:77]
	v_pk_mul_f32 v[78:79], v[72:73], v[72:73]
	v_pk_mul_f32 v[84:85], v[74:75], v[74:75]
	v_lshl_add_u64 v[80:81], v[146:147], 0, v[80:81]
	v_cvt_pk_bf16_f32 v72, v76, v77
	v_cvt_pk_bf16_f32 v73, v78, v79
	v_cvt_pk_bf16_f32 v74, v82, v83
	v_cvt_pk_bf16_f32 v75, v84, v85
	v_max_f32_e32 v64, 0, v64
	v_max_f32_e32 v65, 0, v65
	global_store_dwordx4 v[80:81], v[72:75], off
	s_nop 1
	v_pk_mul_f32 v[72:73], v[64:65], v[64:65]
	v_max_f32_e32 v66, 0, v66
	v_max_f32_e32 v68, 0, v68
	v_max_f32_e32 v69, 0, v69
	v_max_f32_e32 v64, 0, v70
	v_max_f32_e32 v65, 0, v71
	v_max_f32_e32 v67, 0, v67
	v_pk_mul_f32 v[68:69], v[68:69], v[68:69]
	v_pk_mul_f32 v[70:71], v[64:65], v[64:65]
	v_pk_mul_f32 v[74:75], v[66:67], v[66:67]
	v_cvt_pk_bf16_f32 v64, v68, v69
	v_cvt_pk_bf16_f32 v65, v70, v71
	v_cvt_pk_bf16_f32 v66, v72, v73
	v_cvt_pk_bf16_f32 v67, v74, v75
; __device__ __forceinline__ unsigned cvt_pk_bf16(float lo, float hi) { const f32x2 v = (f32x2){lo, hi}; return __builtin_bit_cast(unsigned, __builtin_convertvector(v, bf16v2)); }
;     __device__ __forceinline__ void operator()(f32x4 (&acc)[2][2][4][2], const Unit& u, int wr, int wc, int fr, int fq, LAS unsigned char* xl, int wid, int lane) const {
;     ...
; #pragma unroll
;         for (int ai = 0; ai < 2; ++ai)
; #pragma unroll
;             for (int m = 0; m < 4; ++m) { bf16_t* rowp = base + (size_t)(row0 + ai * HALF + m * 16) * ldc + col0;
; #pragma unroll
;                 for (int bj = 0; bj < 2; ++bj) { f32x4 v0 = acc[ai][bj][m][0], v1 = acc[ai][bj][m][1];
;                     if (MODE == 2) {
; #pragma unroll
;                         for (int e = 0; e < 4; ++e) { const float a = fmaxf(v0[e], 0.f), b = fmaxf(v1[e], 0.f); v0[e] = a * a; v1[e] = b * b; } }
;                     u32x4 w; w.x = cvt_pk_bf16(v0[0], v0[1]); w.y = cvt_pk_bf16(v0[2], v0[3]); w.z = cvt_pk_bf16(v1[0], v1[1]); w.w = cvt_pk_bf16(v1[2], v1[3]);
;                     *(u32x4*)(rowp + bj * HALF) = w; } }
	v_max_f32_e32 v56, 0, v56
	v_max_f32_e32 v57, 0, v57
	global_store_dwordx4 v[80:81], v[64:67], off offset:256
	s_nop 1
	v_pk_mul_f32 v[66:67], v[56:57], v[56:57]
	v_max_f32_e32 v60, 0, v60
	v_max_f32_e32 v61, 0, v61
	v_max_f32_e32 v58, 0, v58
	v_pk_mul_f32 v[60:61], v[60:61], v[60:61]
	v_max_f32_e32 v56, 0, v62
	v_max_f32_e32 v57, 0, v63
	v_max_f32_e32 v59, 0, v59
	s_mov_b32 s13, 0x100000
	v_pk_mul_f32 v[62:63], v[56:57], v[56:57]
	v_pk_mul_f32 v[68:69], v[58:59], v[58:59]
	v_cvt_pk_bf16_f32 v56, v60, v61
	v_add_co_u32_e32 v60, vcc, s13, v138
	v_cvt_pk_bf16_f32 v57, v62, v63
	v_cvt_pk_bf16_f32 v58, v66, v67
	v_cvt_pk_bf16_f32 v59, v68, v69
	v_addc_co_u32_e32 v61, vcc, 0, v139, vcc
	v_max_f32_e32 v48, 0, v48
	v_max_f32_e32 v49, 0, v49
	global_store_dwordx4 v[60:61], v[56:59], off
	s_nop 1
	v_pk_mul_f32 v[56:57], v[48:49], v[48:49]
	v_max_f32_e32 v50, 0, v50
	v_max_f32_e32 v52, 0, v52
	v_max_f32_e32 v53, 0, v53
	v_max_f32_e32 v48, 0, v54
	v_max_f32_e32 v49, 0, v55
	v_max_f32_e32 v51, 0, v51
	s_mov_b64 s[22:23], 0x100000
	v_pk_mul_f32 v[52:53], v[52:53], v[52:53]
	v_pk_mul_f32 v[54:55], v[48:49], v[48:49]
	v_pk_mul_f32 v[58:59], v[50:51], v[50:51]
	v_lshl_add_u64 v[64:65], v[138:139], 0, s[22:23]
	v_cvt_pk_bf16_f32 v48, v52, v53
	v_cvt_pk_bf16_f32 v49, v54, v55
	v_cvt_pk_bf16_f32 v50, v56, v57
	v_cvt_pk_bf16_f32 v51, v58, v59
	v_max_f32_e32 v40, 0, v40
	v_max_f32_e32 v41, 0, v41
	global_store_dwordx4 v[64:65], v[48:51], off offset:256
	s_nop 1
	v_pk_mul_f32 v[50:51], v[40:41], v[40:41]
	v_max_f32_e32 v44, 0, v44
	v_max_f32_e32 v45, 0, v45
	v_max_f32_e32 v42, 0, v42
	v_pk_mul_f32 v[44:45], v[44:45], v[44:45]
	v_max_f32_e32 v40, 0, v46
	v_max_f32_e32 v41, 0, v47
	v_max_f32_e32 v43, 0, v43
	s_mov_b32 s13, 0x120000
	v_pk_mul_f32 v[46:47], v[40:41], v[40:41]
	v_pk_mul_f32 v[52:53], v[42:43], v[42:43]
	v_cvt_pk_bf16_f32 v40, v44, v45
	v_add_co_u32_e32 v44, vcc, s13, v138
	v_cvt_pk_bf16_f32 v41, v46, v47
	v_cvt_pk_bf16_f32 v42, v50, v51
	v_cvt_pk_bf16_f32 v43, v52, v53
	v_addc_co_u32_e32 v45, vcc, 0, v139, vcc
	v_max_f32_e32 v32, 0, v32
	v_max_f32_e32 v33, 0, v33
	global_store_dwordx4 v[44:45], v[40:43], off
	s_nop 1
	v_pk_mul_f32 v[40:41], v[32:33], v[32:33]
	v_max_f32_e32 v34, 0, v34
	v_max_f32_e32 v36, 0, v36
	v_max_f32_e32 v37, 0, v37
	v_max_f32_e32 v32, 0, v38
	v_max_f32_e32 v33, 0, v39
	v_max_f32_e32 v35, 0, v35
	s_mov_b64 s[22:23], 0x120000
	v_pk_mul_f32 v[36:37], v[36:37], v[36:37]
	v_pk_mul_f32 v[38:39], v[32:33], v[32:33]
	v_pk_mul_f32 v[42:43], v[34:35], v[34:35]
	v_lshl_add_u64 v[48:49], v[138:139], 0, s[22:23]
	v_cvt_pk_bf16_f32 v32, v36, v37
	v_cvt_pk_bf16_f32 v33, v38, v39
	v_cvt_pk_bf16_f32 v34, v40, v41
	v_cvt_pk_bf16_f32 v35, v42, v43
	v_max_f32_e32 v24, 0, v24
	v_max_f32_e32 v25, 0, v25
	global_store_dwordx4 v[48:49], v[32:35], off offset:256
	s_nop 1
	v_pk_mul_f32 v[34:35], v[24:25], v[24:25]
	v_max_f32_e32 v28, 0, v28
	v_max_f32_e32 v29, 0, v29
	v_max_f32_e32 v26, 0, v26
	v_pk_mul_f32 v[28:29], v[28:29], v[28:29]
	v_max_f32_e32 v24, 0, v30
	v_max_f32_e32 v25, 0, v31
	v_max_f32_e32 v27, 0, v27
	s_mov_b32 s13, 0x140000
	v_pk_mul_f32 v[30:31], v[24:25], v[24:25]
	v_pk_mul_f32 v[36:37], v[26:27], v[26:27]
	v_cvt_pk_bf16_f32 v24, v28, v29
	v_add_co_u32_e32 v28, vcc, s13, v138
	v_cvt_pk_bf16_f32 v25, v30, v31
	v_cvt_pk_bf16_f32 v26, v34, v35
	v_cvt_pk_bf16_f32 v27, v36, v37
	v_addc_co_u32_e32 v29, vcc, 0, v139, vcc
	v_max_f32_e32 v16, 0, v16
	v_max_f32_e32 v17, 0, v17
	global_store_dwordx4 v[28:29], v[24:27], off
	s_nop 1
	v_pk_mul_f32 v[24:25], v[16:17], v[16:17]
	v_max_f32_e32 v18, 0, v18
	v_max_f32_e32 v20, 0, v20
	v_max_f32_e32 v21, 0, v21
	v_max_f32_e32 v16, 0, v22
	v_max_f32_e32 v17, 0, v23
	v_max_f32_e32 v19, 0, v19
	s_mov_b64 s[22:23], 0x140000
	v_pk_mul_f32 v[20:21], v[20:21], v[20:21]
	v_pk_mul_f32 v[22:23], v[16:17], v[16:17]
	v_pk_mul_f32 v[26:27], v[18:19], v[18:19]
	v_lshl_add_u64 v[32:33], v[138:139], 0, s[22:23]
	v_cvt_pk_bf16_f32 v16, v20, v21
	v_cvt_pk_bf16_f32 v17, v22, v23
	v_cvt_pk_bf16_f32 v18, v24, v25
	v_cvt_pk_bf16_f32 v19, v26, v27
	v_max_f32_e32 v8, 0, v8
	v_max_f32_e32 v9, 0, v9
	global_store_dwordx4 v[32:33], v[16:19], off offset:256
	s_nop 1
	v_pk_mul_f32 v[18:19], v[8:9], v[8:9]
	v_max_f32_e32 v12, 0, v12
	v_max_f32_e32 v13, 0, v13
	v_max_f32_e32 v10, 0, v10
	v_pk_mul_f32 v[12:13], v[12:13], v[12:13]
	v_max_f32_e32 v8, 0, v14
	v_max_f32_e32 v9, 0, v15
	v_max_f32_e32 v11, 0, v11
	s_mov_b32 s13, 0x160000
	v_pk_mul_f32 v[14:15], v[8:9], v[8:9]
	v_pk_mul_f32 v[20:21], v[10:11], v[10:11]
	v_cvt_pk_bf16_f32 v8, v12, v13
	v_add_co_u32_e32 v12, vcc, s13, v138
	v_cvt_pk_bf16_f32 v9, v14, v15
	v_cvt_pk_bf16_f32 v10, v18, v19
	v_cvt_pk_bf16_f32 v11, v20, v21
	v_addc_co_u32_e32 v13, vcc, 0, v139, vcc
	v_max_f32_e32 v0, 0, v0
	v_max_f32_e32 v1, 0, v1
	global_store_dwordx4 v[12:13], v[8:11], off
	s_nop 1
	v_pk_mul_f32 v[8:9], v[0:1], v[0:1]
	v_max_f32_e32 v2, 0, v2
	v_max_f32_e32 v4, 0, v4
	v_max_f32_e32 v5, 0, v5
	v_max_f32_e32 v0, 0, v6
	v_max_f32_e32 v1, 0, v7
	v_max_f32_e32 v3, 0, v3
	s_mov_b64 s[22:23], 0x160000
	v_pk_mul_f32 v[4:5], v[4:5], v[4:5]
	v_pk_mul_f32 v[6:7], v[0:1], v[0:1]
	v_pk_mul_f32 v[10:11], v[2:3], v[2:3]
	v_lshl_add_u64 v[16:17], v[138:139], 0, s[22:23]
	v_cvt_pk_bf16_f32 v0, v4, v5
	v_cvt_pk_bf16_f32 v1, v6, v7
	v_cvt_pk_bf16_f32 v2, v8, v9
	v_cvt_pk_bf16_f32 v3, v10, v11
	s_and_b64 vcc, exec, s[4:5]
	s_mov_b64 s[4:5], -1
	global_store_dwordx4 v[16:17], v[0:3], off offset:256
	s_cbranch_vccnz .LBB0_177
	s_andn2_b64 vcc, exec, s[6:7]
	s_cbranch_vccnz .LBB0_176
	s_barrier
	s_branch .LBB0_176

; #define LAS __attribute__((address_space(3)))
; __device__ __forceinline__ int kswz(int key) { return ((key >> 1) & 1) | (((key >> 3) & 3) << 1); }
; #define AH_LDK(c, bufi) do { kf[bufi][0] = *(const LAS bf16x8*)(lds + kaddr0 + (c) * kcs); kf[bufi][1] = *(const LAS bf16x8*)(lds + kaddr1 + (c) * kcs); \
;         kf[bufi][2] = *(const LAS bf16x8*)(lds + kaddr0 + (c) * kcs + 512); kf[bufi][3] = *(const LAS bf16x8*)(lds + kaddr1 + (c) * kcs + 512); } while (0)
; template <bool LOC> ...
;     ...
;     AH_LDK(0, 0);
; #pragma unroll
;     for (int c = 0; c < 8; ++c) {
;         if (c < 7) AH_LDK(c + 1, (c + 1) & 1);
;         __builtin_amdgcn_sched_barrier(0);
;         f32x4 t0 = (f32x4){0.f, 0.f, 0.f, 0.f}, t1 = (f32x4){0.f, 0.f, 0.f, 0.f};
;         t0 = __builtin_amdgcn_mfma_f32_16x16x32_bf16(kf[c & 1][0], q0, t0, 0, 0, 0); t1 = __builtin_amdgcn_mfma_f32_16x16x32_bf16(kf[c & 1][2], q0, t1, 0, 0, 0);
;         t0 = __builtin_amdgcn_mfma_f32_16x16x32_bf16(kf[c & 1][1], q1, t0, 0, 0, 0); t1 = __builtin_amdgcn_mfma_f32_16x16x32_bf16(kf[c & 1][3], q1, t1, 0, 0, 0);
; #pragma unroll
;         for (int e = 0; e < 8; ++e) { const float a = (e < 4) ? t0[e] : t1[e - 4];
;             if (LOC) { const float bv = bp[c * RPB_PITCH + e]; const bool ok = (e >= elo) && (e < elo + 16); s[c][e] = ok ? (a * SC + bv) : -INFINITY; }
;             else s[c][e] = a * SC; }
;         __builtin_amdgcn_sched_barrier(0);
;     }
; __device__ __forceinline__ void phase_mixer(const Params& p, LAS unsigned char* lds, int l, bool with_ctx, int G, int tid, int wave, int lane, int rep_attn, int rep_pool) {
;     ...
;             const int kl = (rs - rs0) * 64 + kc0 + kap, ka0 = AT_KL + kl * 128 + ((g ^ kswz(kl)) << 4), ka1 = AT_KL + kl * 128 + (((g + 4) ^ kswz(kl)) << 4);
;             const int vrow = AT_VL + qi * AT_VLP, vch0 = (rs - rs0) * 8 + (kc0 >> 3);
;             const LAS float* bp = (const LAS float*)(lds + AT_RPB) + (rs - r + 7) * RPB_PITCH + RPB_OFF + (kc0 + 8 * g - qc + 15);
;             attn_half<true>(lds, ka0, ka1, 64 * 128, vrow, vch0, 8, 16 * AT_VLP, bp, qs - kc0 - 8 * g, qA0, qA1, mxA, lA, oA, g, qi);
.LBB0_296:
	s_or_b64 exec, exec, s[68:69]
	v_mov_b32_e32 v216, 0x3e38aa3b
	v_mov_b32_e32 v217, 0x3e38aa3b
	s_add_i32 s64, s64, -4
	s_min_u32 s64, s64, 56
	v_sub_u32_e32 v36, s64, v26
	v_lshl_add_u32 v24, v36, 13, v128
	v_add_u32_e32 v25, v24, v126
	s_waitcnt lgkmcnt(0)
	s_barrier
	v_add_u32_e32 v26, v24, v127
	ds_read_b128 v[30:33], v25
	ds_read_b128 v[38:41], v25 offset:512
	ds_read_b128 v[42:45], v26
	ds_read_b128 v[46:49], v26 offset:512
	ds_read_b128 v[50:53], v25 offset:8192
	ds_read_b128 v[54:57], v25 offset:8704
	ds_read_b128 v[58:61], v26 offset:8192
	ds_read_b128 v[62:65], v26 offset:8704
	s_sub_i32 s63, s64, s63
	v_lshl_add_u32 v24, s63, 8, v129
	v_add_u32_e32 v235, 0x77c, v24
	v_add_u32_e32 v236, 0xb7c, v24
	s_waitcnt lgkmcnt(7)
	v_mfma_f32_16x16x32_bf16 v[30:33], v[30:33], v[4:7], 0
	ds_read2_b32 v[34:35], v235 offset0:0 offset1:1
	s_waitcnt lgkmcnt(5)
	v_mfma_f32_16x16x32_bf16 v[30:33], v[42:45], v[0:3], v[30:33]
	v_mfma_f32_16x16x32_bf16 v[38:41], v[38:41], v[4:7], 0
	v_mfma_f32_16x16x32_bf16 v[38:41], v[46:49], v[0:3], v[38:41]
	ds_read2_b32 v[238:239], v235 offset0:2 offset1:3
	ds_read2_b32 v[240:241], v235 offset0:4 offset1:5
	ds_read2_b32 v[242:243], v235 offset0:6 offset1:7
	s_waitcnt lgkmcnt(0)
	s_nop 3
	v_pk_fma_f32 v[34:35], v[30:31], v[216:217], v[34:35]
	v_cndmask_b32_e64 v30, v222, v34, s[6:7]
	v_cndmask_b32_e64 v29, v222, v35, s[8:9]
	v_pk_fma_f32 v[238:239], v[32:33], v[216:217], v[238:239]
	v_cndmask_b32_e64 v32, v222, v238, s[10:11]
	v_cndmask_b32_e64 v31, v222, v239, s[12:13]
	v_pk_fma_f32 v[240:241], v[38:39], v[216:217], v[240:241]
	v_cndmask_b32_e64 v34, v222, v240, s[14:15]
	v_cndmask_b32_e64 v33, v222, v241, s[16:17]
	v_pk_fma_f32 v[242:243], v[40:41], v[216:217], v[242:243]
	v_cndmask_b32_e64 v43, v222, v242, s[18:19]
	v_cndmask_b32_e64 v41, v222, v243, s[20:21]
	ds_read_b128 v[44:47], v25 offset:16384
	ds_read_b128 v[66:69], v25 offset:16896
	ds_read_b128 v[100:103], v26 offset:16384
	ds_read_b128 v[152:155], v26 offset:16896
	v_mfma_f32_16x16x32_bf16 v[48:51], v[50:53], v[4:7], 0
	ds_read2_b32 v[38:39], v235 offset0:64 offset1:65
	v_mfma_f32_16x16x32_bf16 v[48:51], v[58:61], v[0:3], v[48:51]
	v_mfma_f32_16x16x32_bf16 v[52:55], v[54:57], v[4:7], 0
	v_mfma_f32_16x16x32_bf16 v[52:55], v[62:65], v[0:3], v[52:55]
	ds_read2_b32 v[238:239], v235 offset0:66 offset1:67
	ds_read2_b32 v[240:241], v235 offset0:68 offset1:69
	ds_read2_b32 v[242:243], v235 offset0:70 offset1:71
	s_waitcnt lgkmcnt(0)
	s_nop 4
	v_pk_fma_f32 v[38:39], v[48:49], v[216:217], v[38:39]
	v_cndmask_b32_e64 v37, v222, v38, s[6:7]
	v_cndmask_b32_e64 v35, v222, v39, s[8:9]
	v_pk_fma_f32 v[238:239], v[50:51], v[216:217], v[238:239]
	v_cndmask_b32_e64 v39, v222, v238, s[10:11]
	v_cndmask_b32_e64 v38, v222, v239, s[12:13]
	v_pk_fma_f32 v[240:241], v[52:53], v[216:217], v[240:241]
	v_cndmask_b32_e64 v42, v222, v240, s[14:15]
	v_cndmask_b32_e64 v40, v222, v241, s[16:17]
	v_pk_fma_f32 v[242:243], v[54:55], v[216:217], v[242:243]
	v_cndmask_b32_e64 v51, v222, v242, s[18:19]
	v_cndmask_b32_e64 v49, v222, v243, s[20:21]
	ds_read_b128 v[52:55], v25 offset:24576
	ds_read_b128 v[60:63], v25 offset:25088
	ds_read_b128 v[170:173], v26 offset:24576
	ds_read_b128 v[174:177], v26 offset:25088
	v_mfma_f32_16x16x32_bf16 v[44:47], v[44:47], v[4:7], 0
	v_mfma_f32_16x16x32_bf16 v[56:59], v[66:69], v[4:7], 0
	v_mfma_f32_16x16x32_bf16 v[64:67], v[100:103], v[0:3], v[44:47]
	s_nop 4
	ds_read2_b32 v[46:47], v235 offset0:128 offset1:129
	v_mfma_f32_16x16x32_bf16 v[68:71], v[152:155], v[0:3], v[56:59]
	ds_read2_b32 v[238:239], v235 offset0:130 offset1:131
	ds_read2_b32 v[240:241], v235 offset0:132 offset1:133
	ds_read2_b32 v[242:243], v235 offset0:134 offset1:135
	s_waitcnt lgkmcnt(0)
	v_pk_fma_f32 v[46:47], v[64:65], v[216:217], v[46:47]
	v_cndmask_b32_e64 v45, v222, v46, s[6:7]
	v_cndmask_b32_e64 v44, v222, v47, s[8:9]
	v_pk_fma_f32 v[238:239], v[66:67], v[216:217], v[238:239]
	v_cndmask_b32_e64 v47, v222, v238, s[10:11]
	v_cndmask_b32_e64 v46, v222, v239, s[12:13]
	v_pk_fma_f32 v[240:241], v[68:69], v[216:217], v[240:241]
	v_cndmask_b32_e64 v50, v222, v240, s[14:15]
	v_cndmask_b32_e64 v48, v222, v241, s[16:17]
	v_pk_fma_f32 v[242:243], v[70:71], v[216:217], v[242:243]
	v_cndmask_b32_e64 v59, v222, v242, s[18:19]
	v_cndmask_b32_e64 v57, v222, v243, s[20:21]
	ds_read_b128 v[68:71], v25 offset:32768
	ds_read_b128 v[100:103], v25 offset:33280
	ds_read_b128 v[152:155], v26 offset:32768
	ds_read_b128 v[178:181], v26 offset:33280
	v_mfma_f32_16x16x32_bf16 v[52:55], v[52:55], v[4:7], 0
	v_mfma_f32_16x16x32_bf16 v[64:67], v[170:173], v[0:3], v[52:55]
	v_mfma_f32_16x16x32_bf16 v[60:63], v[60:63], v[4:7], 0
	s_nop 4
	ds_read2_b32 v[54:55], v235 offset0:192 offset1:193
	ds_read2_b32 v[238:239], v235 offset0:194 offset1:195
	ds_read2_b32 v[240:241], v235 offset0:196 offset1:197
	ds_read2_b32 v[242:243], v235 offset0:198 offset1:199
	s_waitcnt lgkmcnt(0)
	v_pk_fma_f32 v[54:55], v[64:65], v[216:217], v[54:55]
	v_cndmask_b32_e64 v53, v222, v54, s[6:7]
	v_cndmask_b32_e64 v52, v222, v55, s[8:9]
	v_mfma_f32_16x16x32_bf16 v[60:63], v[174:177], v[0:3], v[60:63]
	v_pk_fma_f32 v[238:239], v[66:67], v[216:217], v[238:239]
	v_cndmask_b32_e64 v55, v222, v238, s[10:11]
	v_cndmask_b32_e64 v54, v222, v239, s[12:13]
	s_nop 3
	s_nop 0
	v_pk_fma_f32 v[240:241], v[60:61], v[216:217], v[240:241]
	v_cndmask_b32_e64 v58, v222, v240, s[14:15]
	v_cndmask_b32_e64 v56, v222, v241, s[16:17]
	v_pk_fma_f32 v[242:243], v[62:63], v[216:217], v[242:243]
	v_cndmask_b32_e64 v67, v222, v242, s[18:19]
	v_cndmask_b32_e64 v65, v222, v243, s[20:21]
	ds_read_b128 v[170:173], v25 offset:40960
	ds_read_b128 v[174:177], v25 offset:41472
	ds_read_b128 v[182:185], v26 offset:40960
	ds_read_b128 v[186:189], v26 offset:41472
	v_mfma_f32_16x16x32_bf16 v[60:63], v[68:71], v[4:7], 0
	v_mfma_f32_16x16x32_bf16 v[68:71], v[100:103], v[4:7], 0
	v_mfma_f32_16x16x32_bf16 v[100:103], v[152:155], v[0:3], v[60:63]
	s_nop 4
	ds_read2_b32 v[62:63], v236 offset0:0 offset1:1
	v_mfma_f32_16x16x32_bf16 v[68:71], v[178:181], v[0:3], v[68:71]
	ds_read2_b32 v[238:239], v236 offset0:2 offset1:3
	ds_read2_b32 v[240:241], v236 offset0:4 offset1:5
	ds_read2_b32 v[242:243], v236 offset0:6 offset1:7
	s_waitcnt lgkmcnt(0)
; #define AH_LDK(c, bufi) do { kf[bufi][0] = *(const LAS bf16x8*)(lds + kaddr0 + (c) * kcs); kf[bufi][1] = *(const LAS bf16x8*)(lds + kaddr1 + (c) * kcs); \
;         kf[bufi][2] = *(const LAS bf16x8*)(lds + kaddr0 + (c) * kcs + 512); kf[bufi][3] = *(const LAS bf16x8*)(lds + kaddr1 + (c) * kcs + 512); } while (0)
; template <bool LOC> ...
;     ...
;     for (int c = 0; c < 8; ++c) {
;         if (c < 7) AH_LDK(c + 1, (c + 1) & 1);
;         __builtin_amdgcn_sched_barrier(0);
;         f32x4 t0 = (f32x4){0.f, 0.f, 0.f, 0.f}, t1 = (f32x4){0.f, 0.f, 0.f, 0.f};
;         t0 = __builtin_amdgcn_mfma_f32_16x16x32_bf16(kf[c & 1][0], q0, t0, 0, 0, 0); t1 = __builtin_amdgcn_mfma_f32_16x16x32_bf16(kf[c & 1][2], q0, t1, 0, 0, 0);
;         t0 = __builtin_amdgcn_mfma_f32_16x16x32_bf16(kf[c & 1][1], q1, t0, 0, 0, 0); t1 = __builtin_amdgcn_mfma_f32_16x16x32_bf16(kf[c & 1][3], q1, t1, 0, 0, 0);
; #pragma unroll
;         for (int e = 0; e < 8; ++e) { const float a = (e < 4) ? t0[e] : t1[e - 4];
;             if (LOC) { const float bv = bp[c * RPB_PITCH + e]; const bool ok = (e >= elo) && (e < elo + 16); s[c][e] = ok ? (a * SC + bv) : -INFINITY; }
;             else s[c][e] = a * SC; }
;         __builtin_amdgcn_sched_barrier(0);
;     }
;     ...
;     float m2 = mx;
; #pragma unroll
;     for (int c = 0; c < 8; ++c)
; #pragma unroll
;         for (int e = 0; e < 8; ++e) m2 = fmaxf(m2, s[c][e]);
;     m2 = fmaxf(m2, __shfl_xor(m2, 16)); m2 = fmaxf(m2, __shfl_xor(m2, 32));
	v_pk_fma_f32 v[62:63], v[100:101], v[216:217], v[62:63]
	v_cndmask_b32_e64 v61, v222, v62, s[6:7]
	v_cndmask_b32_e64 v60, v222, v63, s[8:9]
	v_pk_fma_f32 v[238:239], v[102:103], v[216:217], v[238:239]
	v_cndmask_b32_e64 v63, v222, v238, s[10:11]
	v_cndmask_b32_e64 v62, v222, v239, s[12:13]
	v_pk_fma_f32 v[240:241], v[68:69], v[216:217], v[240:241]
	v_cndmask_b32_e64 v66, v222, v240, s[14:15]
	v_cndmask_b32_e64 v64, v222, v241, s[16:17]
	v_pk_fma_f32 v[242:243], v[70:71], v[216:217], v[242:243]
	v_cndmask_b32_e64 v102, v222, v242, s[18:19]
	v_cndmask_b32_e64 v100, v222, v243, s[20:21]
	ds_read_b128 v[178:181], v25 offset:49152
	ds_read_b128 v[190:193], v25 offset:49664
	ds_read_b128 v[194:197], v26 offset:49152
	ds_read_b128 v[198:201], v26 offset:49664
	v_mfma_f32_16x16x32_bf16 v[68:71], v[170:173], v[4:7], 0
	v_mfma_f32_16x16x32_bf16 v[170:173], v[182:185], v[0:3], v[68:71]
	v_mfma_f32_16x16x32_bf16 v[152:155], v[174:177], v[4:7], 0
	s_nop 4
	ds_read2_b32 v[70:71], v236 offset0:64 offset1:65
	ds_read2_b32 v[238:239], v236 offset0:66 offset1:67
	ds_read2_b32 v[240:241], v236 offset0:68 offset1:69
	ds_read2_b32 v[242:243], v236 offset0:70 offset1:71
	s_waitcnt lgkmcnt(0)
	v_pk_fma_f32 v[70:71], v[170:171], v[216:217], v[70:71]
	v_cndmask_b32_e64 v69, v222, v70, s[6:7]
	v_cndmask_b32_e64 v68, v222, v71, s[8:9]
	v_mfma_f32_16x16x32_bf16 v[174:177], v[186:189], v[0:3], v[152:155]
	v_pk_fma_f32 v[238:239], v[172:173], v[216:217], v[238:239]
	v_cndmask_b32_e64 v71, v222, v238, s[10:11]
	v_cndmask_b32_e64 v70, v222, v239, s[12:13]
	s_nop 3
	s_nop 0
	v_pk_fma_f32 v[240:241], v[174:175], v[216:217], v[240:241]
	v_cndmask_b32_e64 v101, v222, v240, s[14:15]
	v_cndmask_b32_e64 v99, v222, v241, s[16:17]
	v_pk_fma_f32 v[242:243], v[176:177], v[216:217], v[242:243]
	v_cndmask_b32_e64 v155, v222, v242, s[18:19]
	v_cndmask_b32_e64 v153, v222, v243, s[20:21]
	ds_read_b128 v[182:185], v25 offset:57344
	ds_read_b128 v[186:189], v25 offset:57856
	ds_read_b128 v[202:205], v26 offset:57344
	ds_read_b128 v[206:209], v26 offset:57856
	v_mfma_f32_16x16x32_bf16 v[170:173], v[178:181], v[4:7], 0
	ds_read2_b32 v[26:27], v236 offset0:128 offset1:129
	v_mfma_f32_16x16x32_bf16 v[170:173], v[194:197], v[0:3], v[170:173]
	v_mfma_f32_16x16x32_bf16 v[174:177], v[190:193], v[4:7], 0
	v_mfma_f32_16x16x32_bf16 v[174:177], v[198:201], v[0:3], v[174:177]
	ds_read2_b32 v[238:239], v236 offset0:130 offset1:131
	ds_read2_b32 v[240:241], v236 offset0:132 offset1:133
	ds_read2_b32 v[242:243], v236 offset0:134 offset1:135
	s_waitcnt lgkmcnt(0)
	s_nop 4
	v_pk_fma_f32 v[26:27], v[170:171], v[216:217], v[26:27]
	v_cndmask_b32_e64 v104, v222, v26, s[6:7]
	v_cndmask_b32_e64 v103, v222, v27, s[8:9]
	v_pk_fma_f32 v[238:239], v[172:173], v[216:217], v[238:239]
	v_cndmask_b32_e64 v151, v222, v238, s[10:11]
	v_cndmask_b32_e64 v105, v222, v239, s[12:13]
	v_pk_fma_f32 v[240:241], v[174:175], v[216:217], v[240:241]
	v_cndmask_b32_e64 v154, v222, v240, s[14:15]
	v_cndmask_b32_e64 v152, v222, v241, s[16:17]
	v_pk_fma_f32 v[242:243], v[176:177], v[216:217], v[242:243]
	v_cndmask_b32_e64 v175, v222, v242, s[18:19]
	v_cndmask_b32_e64 v173, v222, v243, s[20:21]
	v_mfma_f32_16x16x32_bf16 v[176:179], v[182:185], v[4:7], 0
	v_mfma_f32_16x16x32_bf16 v[4:7], v[186:189], v[4:7], 0
	v_mfma_f32_16x16x32_bf16 v[176:179], v[202:205], v[0:3], v[176:179]
	v_mfma_f32_16x16x32_bf16 v[0:3], v[206:209], v[0:3], v[4:7]
	s_nop 5
	ds_read2_b32 v[4:5], v236 offset0:192 offset1:193
	ds_read2_b32 v[238:239], v236 offset0:194 offset1:195
	ds_read2_b32 v[240:241], v236 offset0:196 offset1:197
	ds_read2_b32 v[242:243], v236 offset0:198 offset1:199
	s_waitcnt lgkmcnt(0)
	v_pk_fma_f32 v[4:5], v[176:177], v[216:217], v[4:5]
	v_cndmask_b32_e64 v170, v222, v4, s[6:7]
	v_cndmask_b32_e64 v167, v222, v5, s[8:9]
	v_pk_fma_f32 v[238:239], v[178:179], v[216:217], v[238:239]
	v_cndmask_b32_e64 v172, v222, v238, s[10:11]
	v_cndmask_b32_e64 v171, v222, v239, s[12:13]
	v_pk_fma_f32 v[240:241], v[0:1], v[216:217], v[240:241]
	v_cndmask_b32_e64 v176, v222, v240, s[14:15]
	v_cndmask_b32_e64 v174, v222, v241, s[16:17]
	v_pk_fma_f32 v[242:243], v[2:3], v[216:217], v[242:243]
	v_cndmask_b32_e64 v178, v222, v242, s[18:19]
	v_cndmask_b32_e64 v177, v222, v243, s[20:21]
	v_max3_f32 v0, v97, v30, v29
	v_max3_f32 v0, v0, v32, v31
	v_max3_f32 v0, v0, v34, v33
	v_max3_f32 v0, v0, v43, v41
	v_max3_f32 v0, v0, v37, v35
	v_max3_f32 v0, v0, v39, v38
	v_max3_f32 v0, v0, v42, v40
	v_max3_f32 v0, v0, v51, v49
	v_max3_f32 v0, v0, v45, v44
	v_max3_f32 v0, v0, v47, v46
	v_max3_f32 v0, v0, v50, v48
	v_max3_f32 v0, v0, v59, v57
	v_max3_f32 v0, v0, v53, v52
	v_max3_f32 v0, v0, v55, v54
	v_max3_f32 v0, v0, v58, v56
	v_max3_f32 v0, v0, v67, v65
	v_max3_f32 v0, v0, v61, v60
	v_max3_f32 v0, v0, v63, v62
	v_max3_f32 v0, v0, v66, v64
	v_max3_f32 v0, v0, v102, v100
	v_max3_f32 v0, v0, v69, v68
	v_max3_f32 v0, v0, v71, v70
	v_max3_f32 v0, v0, v101, v99
	v_max3_f32 v0, v0, v155, v153
	v_max3_f32 v0, v0, v104, v103
	v_max3_f32 v0, v0, v151, v105
	v_max3_f32 v0, v0, v154, v152
	v_max3_f32 v0, v0, v175, v173
	v_max3_f32 v0, v0, v170, v167
	v_max3_f32 v0, v0, v172, v171
	v_max3_f32 v0, v0, v176, v174
	v_max3_f32 v0, v0, v178, v177
	ds_bpermute_b32 v1, v114, v0
	s_waitcnt lgkmcnt(0)
	v_max_f32_e32 v1, v1, v1
	v_max_f32_e32 v0, v0, v1
	ds_bpermute_b32 v1, v115, v0
	s_waitcnt lgkmcnt(0)
; __device__ __forceinline__ unsigned cvt_pk_bf16(float lo, float hi) { const f32x2 v = (f32x2){lo, hi}; return __builtin_bit_cast(unsigned, __builtin_convertvector(v, bf16v2)); }
; #define AH_LDV(c, bufi) do { const int vaddr = vrow + (((vchunk0 + (c) * vcs + g) ^ qi) << 4); _Pragma("unroll") for (int dt = 0; dt < 4; ++dt) vf[bufi][dt] = *(const LAS bf16x8*)(lds + vaddr + dt * vpitch_dt); } while (0)
; template <bool LOC> ...
;     ...
;     const float alpha = __builtin_amdgcn_exp2f(mx - m2);
;     mx = m2; lsum *= alpha;
; #pragma unroll
;     for (int dt = 0; dt < 4; ++dt) o[dt] = o[dt] * alpha;
;     bf16x8 vf[2][4];
;     ...
;     AH_LDV(0, 0);
; #pragma unroll
;     for (int c = 0; c < 8; ++c) {
;         if (c < 7) AH_LDV(c + 1, (c + 1) & 1);
;         __builtin_amdgcn_sched_barrier(0);
;         float pe[8];
; #pragma unroll
;         for (int e = 0; e < 8; ++e) { pe[e] = __builtin_amdgcn_exp2f(s[c][e] - mx); lsum += pe[e]; }
;         u32x4 pw; pw.x = cvt_pk_bf16(pe[0], pe[1]); pw.y = cvt_pk_bf16(pe[2], pe[3]); pw.z = cvt_pk_bf16(pe[4], pe[5]); pw.w = cvt_pk_bf16(pe[6], pe[7]);
;         const bf16x8 pb = __builtin_bit_cast(bf16x8, pw);
; #pragma unroll
;         for (int dt = 0; dt < 4; ++dt) o[dt] = __builtin_amdgcn_mfma_f32_16x16x32_bf16(vf[c & 1][dt], pb, o[dt], 0, 0, 0);
;         __builtin_amdgcn_sched_barrier(0);
;     }
	v_max_f32_e32 v1, v1, v1
	v_max_f32_e32 v179, v0, v1
	v_sub_f32_e32 v0, v97, v179
	v_exp_f32_e32 v204, v0
	s_nop 0
	v_pk_mul_f32 v[24:25], v[8:9], v[204:205] op_sel_hi:[1,0]
	v_pk_mul_f32 v[8:9], v[12:13], v[204:205] op_sel_hi:[1,0]
	v_lshl_add_u32 v12, v36, 3, v112
	v_xor_b32_e32 v13, v12, v107
	v_lshl_add_u32 v13, v13, 4, v113
	v_pk_mul_f32 v[26:27], v[10:11], v[204:205] op_sel_hi:[1,0]
	v_pk_mul_f32 v[10:11], v[14:15], v[204:205] op_sel_hi:[1,0]
	v_pk_mul_f32 v[6:7], v[18:19], v[204:205] op_sel_hi:[1,0]
	v_pk_mul_f32 v[4:5], v[16:17], v[204:205] op_sel_hi:[1,0]
	v_pk_mul_f32 v[0:1], v[20:21], v[204:205] op_sel_hi:[1,0]
	ds_read_b128 v[14:17], v13
	ds_read_b128 v[18:21], v13 offset:20480
	ds_read_b128 v[180:183], v13 offset:40960
	ds_read_b128 v[184:187], v13 offset:61440
	v_add_u32_e32 v13, 8, v12
	v_xor_b32_e32 v13, v13, v107
	v_lshl_add_u32 v13, v13, 4, v113
	ds_read_b128 v[188:191], v13
	ds_read_b128 v[192:195], v13 offset:20480
	ds_read_b128 v[196:199], v13 offset:40960
	ds_read_b128 v[200:203], v13 offset:61440
	v_pk_mul_f32 v[2:3], v[22:23], v[204:205] op_sel_hi:[1,0]
	v_mul_f32_e32 v218, v28, v204
	v_mov_b32_e32 v219, 0
	v_sub_f32_e32 v224, v30, v179
	v_sub_f32_e32 v225, v29, v179
	v_exp_f32_e32 v224, v224
	v_sub_f32_e32 v226, v32, v179
	v_exp_f32_e32 v225, v225
	v_sub_f32_e32 v227, v31, v179
	v_exp_f32_e32 v226, v226
	v_sub_f32_e32 v228, v34, v179
	v_exp_f32_e32 v227, v227
	v_sub_f32_e32 v229, v33, v179
	v_exp_f32_e32 v228, v228
	v_pk_add_f32 v[218:219], v[218:219], v[224:225]
	v_sub_f32_e32 v230, v43, v179
	v_exp_f32_e32 v229, v229
	v_pk_add_f32 v[218:219], v[218:219], v[226:227]
	v_sub_f32_e32 v231, v41, v179
	v_exp_f32_e32 v230, v230
	v_cvt_pk_bf16_f32 v28, v224, v225
	v_exp_f32_e32 v231, v231
	v_cvt_pk_bf16_f32 v29, v226, v227
	v_pk_add_f32 v[218:219], v[218:219], v[228:229]
	v_cvt_pk_bf16_f32 v30, v228, v229
	v_cvt_pk_bf16_f32 v31, v230, v231
	v_pk_add_f32 v[218:219], v[218:219], v[230:231]
	s_waitcnt lgkmcnt(4)
	v_mfma_f32_16x16x32_bf16 v[14:17], v[14:17], v[28:31], v[24:27]
	v_mfma_f32_16x16x32_bf16 v[8:11], v[18:21], v[28:31], v[8:11]
	v_mfma_f32_16x16x32_bf16 v[4:7], v[180:183], v[28:31], v[4:7]
	v_mfma_f32_16x16x32_bf16 v[0:3], v[184:187], v[28:31], v[0:3]
	v_add_u32_e32 v13, 16, v12
	v_xor_b32_e32 v13, v13, v107
	v_lshl_add_u32 v13, v13, 4, v113
	ds_read_b128 v[18:21], v13
	ds_read_b128 v[22:25], v13 offset:20480
	ds_read_b128 v[26:29], v13 offset:40960
	ds_read_b128 v[30:33], v13 offset:61440
	v_sub_f32_e32 v224, v37, v179
	v_sub_f32_e32 v225, v35, v179
	v_exp_f32_e32 v224, v224
	v_sub_f32_e32 v226, v39, v179
	v_exp_f32_e32 v225, v225
	v_sub_f32_e32 v227, v38, v179
	v_exp_f32_e32 v226, v226
	v_sub_f32_e32 v228, v42, v179
	v_exp_f32_e32 v227, v227
	v_sub_f32_e32 v229, v40, v179
	v_exp_f32_e32 v228, v228
	v_pk_add_f32 v[218:219], v[218:219], v[224:225]
	v_sub_f32_e32 v230, v51, v179
	v_exp_f32_e32 v229, v229
	v_pk_add_f32 v[218:219], v[218:219], v[226:227]
	v_sub_f32_e32 v231, v49, v179
	v_exp_f32_e32 v230, v230
	v_cvt_pk_bf16_f32 v34, v224, v225
	v_exp_f32_e32 v231, v231
	v_cvt_pk_bf16_f32 v35, v226, v227
	v_pk_add_f32 v[218:219], v[218:219], v[228:229]
	v_cvt_pk_bf16_f32 v36, v228, v229
	v_cvt_pk_bf16_f32 v37, v230, v231
	v_pk_add_f32 v[218:219], v[218:219], v[230:231]
	s_waitcnt lgkmcnt(4)
	s_nop 0
	v_mfma_f32_16x16x32_bf16 v[14:17], v[188:191], v[34:37], v[14:17]
	v_mfma_f32_16x16x32_bf16 v[8:11], v[192:195], v[34:37], v[8:11]
	v_mfma_f32_16x16x32_bf16 v[4:7], v[196:199], v[34:37], v[4:7]
	v_mfma_f32_16x16x32_bf16 v[0:3], v[200:203], v[34:37], v[0:3]
	v_add_u32_e32 v13, 24, v12
	v_xor_b32_e32 v13, v13, v107
	v_lshl_add_u32 v13, v13, 4, v113
	ds_read_b128 v[34:37], v13
	ds_read_b128 v[38:41], v13 offset:20480
	ds_read_b128 v[180:183], v13 offset:40960
	ds_read_b128 v[184:187], v13 offset:61440
	v_sub_f32_e32 v224, v45, v179
	v_sub_f32_e32 v225, v44, v179
	v_exp_f32_e32 v224, v224
	v_sub_f32_e32 v226, v47, v179
	v_exp_f32_e32 v225, v225
	v_sub_f32_e32 v227, v46, v179
	v_exp_f32_e32 v226, v226
	v_sub_f32_e32 v228, v50, v179
	v_exp_f32_e32 v227, v227
	v_sub_f32_e32 v229, v48, v179
	v_exp_f32_e32 v228, v228
	v_pk_add_f32 v[218:219], v[218:219], v[224:225]
	v_sub_f32_e32 v230, v59, v179
	v_exp_f32_e32 v229, v229
	v_pk_add_f32 v[218:219], v[218:219], v[226:227]
	v_sub_f32_e32 v231, v57, v179
	v_exp_f32_e32 v230, v230
	v_cvt_pk_bf16_f32 v42, v224, v225
	v_exp_f32_e32 v231, v231
	v_cvt_pk_bf16_f32 v43, v226, v227
	v_pk_add_f32 v[218:219], v[218:219], v[228:229]
	v_cvt_pk_bf16_f32 v44, v228, v229
	v_cvt_pk_bf16_f32 v45, v230, v231
	v_pk_add_f32 v[218:219], v[218:219], v[230:231]
	s_waitcnt lgkmcnt(4)
	s_nop 0
	v_mfma_f32_16x16x32_bf16 v[14:17], v[18:21], v[42:45], v[14:17]
	v_mfma_f32_16x16x32_bf16 v[8:11], v[22:25], v[42:45], v[8:11]
	v_mfma_f32_16x16x32_bf16 v[4:7], v[26:29], v[42:45], v[4:7]
	v_mfma_f32_16x16x32_bf16 v[0:3], v[30:33], v[42:45], v[0:3]
	v_add_u32_e32 v13, 32, v12
	v_xor_b32_e32 v13, v13, v107
	v_lshl_add_u32 v13, v13, 4, v113
	ds_read_b128 v[18:21], v13
	ds_read_b128 v[22:25], v13 offset:20480
	ds_read_b128 v[26:29], v13 offset:40960
	ds_read_b128 v[30:33], v13 offset:61440
	v_sub_f32_e32 v224, v53, v179
	v_sub_f32_e32 v225, v52, v179
	v_exp_f32_e32 v224, v224
	v_sub_f32_e32 v226, v55, v179
	v_exp_f32_e32 v225, v225
	v_sub_f32_e32 v227, v54, v179
	v_exp_f32_e32 v226, v226
	v_sub_f32_e32 v228, v58, v179
	v_exp_f32_e32 v227, v227
	v_sub_f32_e32 v229, v56, v179
	v_exp_f32_e32 v228, v228
	v_pk_add_f32 v[218:219], v[218:219], v[224:225]
	v_sub_f32_e32 v230, v67, v179
	v_exp_f32_e32 v229, v229
	v_pk_add_f32 v[218:219], v[218:219], v[226:227]
	v_sub_f32_e32 v231, v65, v179
	v_exp_f32_e32 v230, v230
	v_cvt_pk_bf16_f32 v42, v224, v225
	v_exp_f32_e32 v231, v231
	v_cvt_pk_bf16_f32 v43, v226, v227
	v_pk_add_f32 v[218:219], v[218:219], v[228:229]
	v_cvt_pk_bf16_f32 v44, v228, v229
	v_cvt_pk_bf16_f32 v45, v230, v231
	v_pk_add_f32 v[218:219], v[218:219], v[230:231]
	s_waitcnt lgkmcnt(4)
; __device__ __forceinline__ unsigned cvt_pk_bf16(float lo, float hi) { const f32x2 v = (f32x2){lo, hi}; return __builtin_bit_cast(unsigned, __builtin_convertvector(v, bf16v2)); }
; #define AH_LDV(c, bufi) do { const int vaddr = vrow + (((vchunk0 + (c) * vcs + g) ^ qi) << 4); _Pragma("unroll") for (int dt = 0; dt < 4; ++dt) vf[bufi][dt] = *(const LAS bf16x8*)(lds + vaddr + dt * vpitch_dt); } while (0)
; template <bool LOC> ...
;     ...
; #pragma unroll
;     for (int c = 0; c < 8; ++c) {
;         if (c < 7) AH_LDV(c + 1, (c + 1) & 1);
;         __builtin_amdgcn_sched_barrier(0);
;         float pe[8];
; #pragma unroll
;         for (int e = 0; e < 8; ++e) { pe[e] = __builtin_amdgcn_exp2f(s[c][e] - mx); lsum += pe[e]; }
;         u32x4 pw; pw.x = cvt_pk_bf16(pe[0], pe[1]); pw.y = cvt_pk_bf16(pe[2], pe[3]); pw.z = cvt_pk_bf16(pe[4], pe[5]); pw.w = cvt_pk_bf16(pe[6], pe[7]);
;         const bf16x8 pb = __builtin_bit_cast(bf16x8, pw);
; #pragma unroll
;         for (int dt = 0; dt < 4; ++dt) o[dt] = __builtin_amdgcn_mfma_f32_16x16x32_bf16(vf[c & 1][dt], pb, o[dt], 0, 0, 0);
;         __builtin_amdgcn_sched_barrier(0);
;     }
	s_nop 0
	v_mfma_f32_16x16x32_bf16 v[14:17], v[34:37], v[42:45], v[14:17]
	v_mfma_f32_16x16x32_bf16 v[8:11], v[38:41], v[42:45], v[8:11]
	v_mfma_f32_16x16x32_bf16 v[4:7], v[180:183], v[42:45], v[4:7]
	v_mfma_f32_16x16x32_bf16 v[0:3], v[184:187], v[42:45], v[0:3]
	v_add_u32_e32 v13, 40, v12
	v_xor_b32_e32 v13, v13, v107
	v_lshl_add_u32 v13, v13, 4, v113
	ds_read_b128 v[34:37], v13
	ds_read_b128 v[38:41], v13 offset:20480
	ds_read_b128 v[42:45], v13 offset:40960
	ds_read_b128 v[46:49], v13 offset:61440
	v_sub_f32_e32 v224, v61, v179
	v_sub_f32_e32 v225, v60, v179
	v_exp_f32_e32 v224, v224
	v_sub_f32_e32 v226, v63, v179
	v_exp_f32_e32 v225, v225
	v_sub_f32_e32 v227, v62, v179
	v_exp_f32_e32 v226, v226
	v_sub_f32_e32 v228, v66, v179
	v_exp_f32_e32 v227, v227
	v_sub_f32_e32 v229, v64, v179
	v_exp_f32_e32 v228, v228
	v_pk_add_f32 v[218:219], v[218:219], v[224:225]
	v_sub_f32_e32 v230, v102, v179
	v_exp_f32_e32 v229, v229
	v_pk_add_f32 v[218:219], v[218:219], v[226:227]
	v_sub_f32_e32 v231, v100, v179
	v_exp_f32_e32 v230, v230
	v_cvt_pk_bf16_f32 v50, v224, v225
	v_exp_f32_e32 v231, v231
	v_cvt_pk_bf16_f32 v51, v226, v227
	v_pk_add_f32 v[218:219], v[218:219], v[228:229]
	v_cvt_pk_bf16_f32 v52, v228, v229
	v_cvt_pk_bf16_f32 v53, v230, v231
	v_pk_add_f32 v[218:219], v[218:219], v[230:231]
	s_waitcnt lgkmcnt(4)
	s_nop 0
	v_mfma_f32_16x16x32_bf16 v[14:17], v[18:21], v[50:53], v[14:17]
	v_mfma_f32_16x16x32_bf16 v[8:11], v[22:25], v[50:53], v[8:11]
	v_mfma_f32_16x16x32_bf16 v[4:7], v[26:29], v[50:53], v[4:7]
	v_mfma_f32_16x16x32_bf16 v[0:3], v[30:33], v[50:53], v[0:3]
	v_add_u32_e32 v13, 48, v12
	v_xor_b32_e32 v13, v13, v107
	v_lshl_add_u32 v13, v13, 4, v113
	ds_read_b128 v[18:21], v13
	ds_read_b128 v[22:25], v13 offset:20480
	ds_read_b128 v[26:29], v13 offset:40960
	ds_read_b128 v[30:33], v13 offset:61440
	v_sub_f32_e32 v224, v69, v179
	v_sub_f32_e32 v225, v68, v179
	v_exp_f32_e32 v224, v224
	v_sub_f32_e32 v226, v71, v179
	v_exp_f32_e32 v225, v225
	v_sub_f32_e32 v227, v70, v179
	v_exp_f32_e32 v226, v226
	v_sub_f32_e32 v228, v101, v179
	v_exp_f32_e32 v227, v227
	v_sub_f32_e32 v229, v99, v179
	v_exp_f32_e32 v228, v228
	v_pk_add_f32 v[218:219], v[218:219], v[224:225]
	v_sub_f32_e32 v230, v155, v179
	v_exp_f32_e32 v229, v229
	v_pk_add_f32 v[218:219], v[218:219], v[226:227]
	v_sub_f32_e32 v231, v153, v179
	v_exp_f32_e32 v230, v230
	v_cvt_pk_bf16_f32 v50, v224, v225
	v_exp_f32_e32 v231, v231
	v_cvt_pk_bf16_f32 v51, v226, v227
	v_pk_add_f32 v[218:219], v[218:219], v[228:229]
	v_cvt_pk_bf16_f32 v52, v228, v229
	v_cvt_pk_bf16_f32 v53, v230, v231
	v_pk_add_f32 v[218:219], v[218:219], v[230:231]
	s_waitcnt lgkmcnt(4)
	s_nop 0
	v_mfma_f32_16x16x32_bf16 v[14:17], v[34:37], v[50:53], v[14:17]
	v_mfma_f32_16x16x32_bf16 v[8:11], v[38:41], v[50:53], v[8:11]
	v_mfma_f32_16x16x32_bf16 v[4:7], v[42:45], v[50:53], v[4:7]
	v_mfma_f32_16x16x32_bf16 v[0:3], v[46:49], v[50:53], v[0:3]
	v_add_u32_e32 v12, 56, v12
	v_xor_b32_e32 v12, v12, v107
	v_lshl_add_u32 v12, v12, 4, v113
	ds_read_b128 v[34:37], v12
	ds_read_b128 v[38:41], v12 offset:20480
	ds_read_b128 v[42:45], v12 offset:40960
	ds_read_b128 v[46:49], v12 offset:61440
	v_sub_f32_e32 v224, v104, v179
	v_sub_f32_e32 v225, v103, v179
	v_exp_f32_e32 v224, v224
	v_sub_f32_e32 v226, v151, v179
	v_exp_f32_e32 v225, v225
	v_sub_f32_e32 v227, v105, v179
	v_exp_f32_e32 v226, v226
	v_sub_f32_e32 v228, v154, v179
	v_exp_f32_e32 v227, v227
	v_sub_f32_e32 v229, v152, v179
	v_exp_f32_e32 v228, v228
	v_pk_add_f32 v[218:219], v[218:219], v[224:225]
	v_sub_f32_e32 v230, v175, v179
	v_exp_f32_e32 v229, v229
	v_pk_add_f32 v[218:219], v[218:219], v[226:227]
	v_sub_f32_e32 v231, v173, v179
	v_exp_f32_e32 v230, v230
	v_cvt_pk_bf16_f32 v50, v224, v225
	v_exp_f32_e32 v231, v231
	v_cvt_pk_bf16_f32 v51, v226, v227
	v_pk_add_f32 v[218:219], v[218:219], v[228:229]
	v_cvt_pk_bf16_f32 v52, v228, v229
	v_cvt_pk_bf16_f32 v53, v230, v231
	v_pk_add_f32 v[218:219], v[218:219], v[230:231]
	s_waitcnt lgkmcnt(4)
; __device__ __forceinline__ unsigned cvt_pk_bf16(float lo, float hi) { const f32x2 v = (f32x2){lo, hi}; return __builtin_bit_cast(unsigned, __builtin_convertvector(v, bf16v2)); }
; #define AH_LDV(c, bufi) do { const int vaddr = vrow + (((vchunk0 + (c) * vcs + g) ^ qi) << 4); _Pragma("unroll") for (int dt = 0; dt < 4; ++dt) vf[bufi][dt] = *(const LAS bf16x8*)(lds + vaddr + dt * vpitch_dt); } while (0)
; template <bool LOC> ...
;     ...
;     for (int c = 0; c < 8; ++c) {
;         if (c < 7) AH_LDV(c + 1, (c + 1) & 1);
;         __builtin_amdgcn_sched_barrier(0);
;         float pe[8];
; #pragma unroll
;         for (int e = 0; e < 8; ++e) { pe[e] = __builtin_amdgcn_exp2f(s[c][e] - mx); lsum += pe[e]; }
;         u32x4 pw; pw.x = cvt_pk_bf16(pe[0], pe[1]); pw.y = cvt_pk_bf16(pe[2], pe[3]); pw.z = cvt_pk_bf16(pe[4], pe[5]); pw.w = cvt_pk_bf16(pe[6], pe[7]);
;         const bf16x8 pb = __builtin_bit_cast(bf16x8, pw);
; #pragma unroll
;         for (int dt = 0; dt < 4; ++dt) o[dt] = __builtin_amdgcn_mfma_f32_16x16x32_bf16(vf[c & 1][dt], pb, o[dt], 0, 0, 0);
;         __builtin_amdgcn_sched_barrier(0);
;     }
;     ...
; }
; __device__ __forceinline__ void attn_store(bf16_t* MIX, int qtok, int h, int g, float lsum, const f32x4 (&o)[4]) {
;     lsum += __shfl_xor(lsum, 16); lsum += __shfl_xor(lsum, 32);
;     const float inv = 1.f / lsum;
;     bf16_t* op = MIX + (size_t)qtok * DM + 512 + h * 64 + 4 * g;
; #pragma unroll
;     for (int dt = 0; dt < 4; ++dt) { u32x2 w; w.x = cvt_pk_bf16(o[dt][0] * inv, o[dt][1] * inv); w.y = cvt_pk_bf16(o[dt][2] * inv, o[dt][3] * inv); *(u32x2*)(op + 16 * dt) = w; }
; }
; __device__ __forceinline__ void phase_mixer(const Params& p, LAS unsigned char* lds, int l, bool with_ctx, int G, int tid, int wave, int lane, int rep_attn, int rep_pool) {
;     ...
;             attn_store(MIX, b * SEQ + r * 64 + 16 * n + qi, h, g, lA, oA);
;         }
;         __syncthreads();
;     }
	v_mfma_f32_16x16x32_bf16 v[12:15], v[18:21], v[50:53], v[14:17]
	v_mfma_f32_16x16x32_bf16 v[8:11], v[22:25], v[50:53], v[8:11]
	v_mfma_f32_16x16x32_bf16 v[4:7], v[26:29], v[50:53], v[4:7]
	v_mfma_f32_16x16x32_bf16 v[0:3], v[30:33], v[50:53], v[0:3]
	v_sub_f32_e32 v224, v170, v179
	v_sub_f32_e32 v225, v167, v179
	v_exp_f32_e32 v224, v224
	v_sub_f32_e32 v226, v172, v179
	v_exp_f32_e32 v225, v225
	v_sub_f32_e32 v227, v171, v179
	v_exp_f32_e32 v226, v226
	v_sub_f32_e32 v228, v176, v179
	v_exp_f32_e32 v227, v227
	v_sub_f32_e32 v229, v174, v179
	v_exp_f32_e32 v228, v228
	v_pk_add_f32 v[218:219], v[218:219], v[224:225]
	v_sub_f32_e32 v230, v178, v179
	v_exp_f32_e32 v229, v229
	v_pk_add_f32 v[218:219], v[218:219], v[226:227]
	v_sub_f32_e32 v231, v177, v179
	v_exp_f32_e32 v230, v230
	v_cvt_pk_bf16_f32 v16, v224, v225
	v_exp_f32_e32 v231, v231
	v_cvt_pk_bf16_f32 v17, v226, v227
	v_pk_add_f32 v[218:219], v[218:219], v[228:229]
	v_cvt_pk_bf16_f32 v18, v228, v229
	v_cvt_pk_bf16_f32 v19, v230, v231
	v_pk_add_f32 v[218:219], v[218:219], v[230:231]
	v_add_f32_e32 v25, v218, v219
	s_waitcnt lgkmcnt(0)
	s_nop 0
	v_mfma_f32_16x16x32_bf16 v[12:15], v[34:37], v[16:19], v[12:15]
	v_mfma_f32_16x16x32_bf16 v[8:11], v[38:41], v[16:19], v[8:11]
	v_mfma_f32_16x16x32_bf16 v[4:7], v[42:45], v[16:19], v[4:7]
	v_mfma_f32_16x16x32_bf16 v[0:3], v[46:49], v[16:19], v[0:3]
	ds_bpermute_b32 v17, v114, v25
	v_or_b32_e32 v16, s62, v108
	v_mov_b32_e32 v99, v157
	s_add_i32 s61, s61, s3
	s_cmpk_gt_i32 s61, 0x7ff
	s_waitcnt lgkmcnt(0)
	v_add_f32_e32 v18, v25, v17
	ds_bpermute_b32 v19, v115, v18
	v_ashrrev_i32_e32 v17, 31, v16
	v_lshlrev_b64 v[16:17], 11, v[16:17]
	v_lshl_add_u64 v[16:17], s[26:27], 0, v[16:17]
	v_lshl_add_u64 v[16:17], v[16:17], 0, s[30:31]
	s_waitcnt lgkmcnt(0)
	v_add_f32_e32 v18, v18, v19
	v_div_scale_f32 v19, s[62:63], v18, v18, 1.0
	v_rcp_f32_e32 v20, v19
	v_div_scale_f32 v21, vcc, 1.0, v18, 1.0
	v_lshl_add_u64 v[16:17], v[16:17], 0, v[98:99]
	v_fma_f32 v22, -v19, v20, 1.0
	v_fmac_f32_e32 v20, v22, v20
	v_mul_f32_e32 v22, v21, v20
	v_fma_f32 v23, -v19, v22, v21
	v_fmac_f32_e32 v22, v23, v20
	v_fma_f32 v19, -v19, v22, v21
	v_div_fmas_f32 v19, v19, v20, v22
	v_div_fixup_f32 v18, v19, v18, 1.0
	v_pk_mul_f32 v[12:13], v[12:13], v[18:19] op_sel_hi:[1,0]
	v_pk_mul_f32 v[14:15], v[14:15], v[18:19] op_sel_hi:[1,0]
	v_pk_mul_f32 v[8:9], v[8:9], v[18:19] op_sel_hi:[1,0]
	v_pk_mul_f32 v[10:11], v[10:11], v[18:19] op_sel_hi:[1,0]
	v_pk_mul_f32 v[4:5], v[4:5], v[18:19] op_sel_hi:[1,0]
	v_pk_mul_f32 v[6:7], v[6:7], v[18:19] op_sel_hi:[1,0]
	v_pk_mul_f32 v[0:1], v[0:1], v[18:19] op_sel_hi:[1,0]
	v_pk_mul_f32 v[2:3], v[2:3], v[18:19] op_sel_hi:[1,0]
	v_cvt_pk_bf16_f32 v12, v12, v13
	v_cvt_pk_bf16_f32 v13, v14, v15
	v_cvt_pk_bf16_f32 v8, v8, v9
	v_cvt_pk_bf16_f32 v9, v10, v11
	v_cvt_pk_bf16_f32 v4, v4, v5
	v_cvt_pk_bf16_f32 v5, v6, v7
	v_cvt_pk_bf16_f32 v0, v0, v1
	v_cvt_pk_bf16_f32 v1, v2, v3
	global_store_dwordx2 v[16:17], v[12:13], off offset:1024
	global_store_dwordx2 v[16:17], v[8:9], off offset:1056
	global_store_dwordx2 v[16:17], v[4:5], off offset:1088
	global_store_dwordx2 v[16:17], v[0:1], off offset:1120
	s_barrier
	s_cbranch_scc1 .LBB0_306

; __device__ __forceinline__ int kswz(int key) { return ((key >> 1) & 1) | (((key >> 3) & 3) << 1); }
; template <bool LOC> ...
;     ...
;     AH_LDK(0, 0);
; #pragma unroll
;     for (int c = 0; c < 8; ++c) {
;         if (c < 7) AH_LDK(c + 1, (c + 1) & 1);
;         __builtin_amdgcn_sched_barrier(0);
;         f32x4 t0 = (f32x4){0.f, 0.f, 0.f, 0.f}, t1 = (f32x4){0.f, 0.f, 0.f, 0.f};
;         t0 = __builtin_amdgcn_mfma_f32_16x16x32_bf16(kf[c & 1][0], q0, t0, 0, 0, 0); t1 = __builtin_amdgcn_mfma_f32_16x16x32_bf16(kf[c & 1][2], q0, t1, 0, 0, 0);
;         t0 = __builtin_amdgcn_mfma_f32_16x16x32_bf16(kf[c & 1][1], q1, t0, 0, 0, 0); t1 = __builtin_amdgcn_mfma_f32_16x16x32_bf16(kf[c & 1][3], q1, t1, 0, 0, 0);
; #pragma unroll
;         for (int e = 0; e < 8; ++e) { const float a = (e < 4) ? t0[e] : t1[e - 4];
;             if (LOC) { const float bv = bp[c * RPB_PITCH + e]; const bool ok = (e >= elo) && (e < elo + 16); s[c][e] = ok ? (a * SC + bv) : -INFINITY; }
;             else s[c][e] = a * SC; }
;         __builtin_amdgcn_sched_barrier(0);
;     }
;     ...
;     float m2 = mx;
; #pragma unroll
;     for (int c = 0; c < 8; ++c)
; #pragma unroll
;         for (int e = 0; e < 8; ++e) m2 = fmaxf(m2, s[c][e]);
;     m2 = fmaxf(m2, __shfl_xor(m2, 16)); m2 = fmaxf(m2, __shfl_xor(m2, 32));
; __device__ __forceinline__ void phase_mixer(const Params& p, LAS unsigned char* lds, int l, bool with_ctx, int G, int tid, int wave, int lane, int rep_attn, int rep_pool) {
;     ...
;         float mxA = -INFINITY, lA = 0.f; f32x4 oA[4]; bf16x8 qA0, qA1;
;         {
;             const int kl = kap, ka0 = AT_KC + kl * 128 + ((g ^ kswz(kl)) << 4), ka1 = AT_KC + kl * 128 + (((g + 4) ^ kswz(kl)) << 4);
;             const int vrow = AT_VC + qi * 512;
; #pragma unroll 1
;             for (int ps = 2 - npass; ps < 2; ++ps) {
;                 const int qtok = (ps == 1) ? (b * SEQ + r * 64 + 16 * n + qi) : (ML + b * CT + 16 * (sel * 8 + wave) + qi);
;                 const bf16_t* qp = PB + (size_t)qtok * PBW + 512 + h * 64 + 8 * g;
;                 qA0 = *(const bf16x8*)qp; qA1 = *(const bf16x8*)(qp + 32);
;                 mxA = -INFINITY; lA = 0.f;
; #pragma unroll
;                 for (int dt = 0; dt < 4; ++dt) oA[dt] = (f32x4){0.f, 0.f, 0.f, 0.f};
;                 attn_half<false>(lds, ka0, ka1, 32 * 128, vrow, 0, 4, 16 * 512, nullptr, 0, qA0, qA1, mxA, lA, oA, g, qi);
.Lqjoin_299:
	ds_read_b128 v[8:11], v132
	ds_read_b128 v[12:15], v132 offset:512
	ds_read_b128 v[16:19], v133
	ds_read_b128 v[20:23], v133 offset:512
	ds_read_b128 v[24:27], v132 offset:4096
	ds_read_b128 v[28:31], v132 offset:4608
	ds_read_b128 v[32:35], v133 offset:4096
	ds_read_b128 v[36:39], v133 offset:4608
	s_waitcnt vmcnt(1) lgkmcnt(7)
	v_mfma_f32_16x16x32_bf16 v[8:11], v[8:11], v[4:7], 0
	s_waitcnt vmcnt(0) lgkmcnt(5)
	v_mfma_f32_16x16x32_bf16 v[68:71], v[16:19], v[0:3], v[8:11]
	v_mfma_f32_16x16x32_bf16 v[8:11], v[12:15], v[4:7], 0
	s_waitcnt lgkmcnt(4)
	v_mfma_f32_16x16x32_bf16 v[64:67], v[20:23], v[0:3], v[8:11]
	s_nop 4
	ds_read_b128 v[8:11], v132 offset:8192
	ds_read_b128 v[12:15], v132 offset:8704
	ds_read_b128 v[16:19], v133 offset:8192
	ds_read_b128 v[20:23], v133 offset:8704
	s_waitcnt lgkmcnt(4)
	v_mfma_f32_16x16x32_bf16 v[24:27], v[24:27], v[4:7], 0
	v_mfma_f32_16x16x32_bf16 v[60:63], v[32:35], v[0:3], v[24:27]
	v_mfma_f32_16x16x32_bf16 v[24:27], v[28:31], v[4:7], 0
	v_mfma_f32_16x16x32_bf16 v[56:59], v[36:39], v[0:3], v[24:27]
	s_nop 4
	ds_read_b128 v[24:27], v132 offset:12288
	ds_read_b128 v[28:31], v132 offset:12800
	ds_read_b128 v[32:35], v133 offset:12288
	ds_read_b128 v[36:39], v133 offset:12800
	s_waitcnt lgkmcnt(4)
	v_mfma_f32_16x16x32_bf16 v[8:11], v[8:11], v[4:7], 0
	v_mfma_f32_16x16x32_bf16 v[52:55], v[16:19], v[0:3], v[8:11]
	v_mfma_f32_16x16x32_bf16 v[8:11], v[12:15], v[4:7], 0
	v_mfma_f32_16x16x32_bf16 v[48:51], v[20:23], v[0:3], v[8:11]
	s_nop 4
	ds_read_b128 v[8:11], v132 offset:16384
	ds_read_b128 v[12:15], v132 offset:16896
	ds_read_b128 v[16:19], v133 offset:16384
	ds_read_b128 v[20:23], v133 offset:16896
	s_waitcnt lgkmcnt(4)
	v_mfma_f32_16x16x32_bf16 v[24:27], v[24:27], v[4:7], 0
	v_mfma_f32_16x16x32_bf16 v[44:47], v[32:35], v[0:3], v[24:27]
	v_mfma_f32_16x16x32_bf16 v[24:27], v[28:31], v[4:7], 0
	v_mfma_f32_16x16x32_bf16 v[40:43], v[36:39], v[0:3], v[24:27]
	s_nop 4
	ds_read_b128 v[24:27], v132 offset:20480
	ds_read_b128 v[152:155], v132 offset:20992
	ds_read_b128 v[28:31], v133 offset:20480
	ds_read_b128 v[170:173], v133 offset:20992
	s_waitcnt lgkmcnt(4)
	v_mfma_f32_16x16x32_bf16 v[8:11], v[8:11], v[4:7], 0
	v_mfma_f32_16x16x32_bf16 v[36:39], v[16:19], v[0:3], v[8:11]
	v_mfma_f32_16x16x32_bf16 v[8:11], v[12:15], v[4:7], 0
	v_mfma_f32_16x16x32_bf16 v[32:35], v[20:23], v[0:3], v[8:11]
	s_nop 4
	ds_read_b128 v[8:11], v132 offset:24576
	ds_read_b128 v[12:15], v132 offset:25088
	ds_read_b128 v[16:19], v133 offset:24576
	ds_read_b128 v[174:177], v133 offset:25088
	s_waitcnt lgkmcnt(4)
	v_mfma_f32_16x16x32_bf16 v[20:23], v[24:27], v[4:7], 0
	v_mfma_f32_16x16x32_bf16 v[28:31], v[28:31], v[0:3], v[20:23]
	v_mfma_f32_16x16x32_bf16 v[20:23], v[152:155], v[4:7], 0
	v_mfma_f32_16x16x32_bf16 v[24:27], v[170:173], v[0:3], v[20:23]
	s_nop 4
	ds_read_b128 v[152:155], v132 offset:28672
	ds_read_b128 v[170:173], v132 offset:29184
	ds_read_b128 v[178:181], v133 offset:28672
	ds_read_b128 v[182:185], v133 offset:29184
	s_waitcnt lgkmcnt(0)
	v_mfma_f32_16x16x32_bf16 v[8:11], v[8:11], v[4:7], 0
	v_mfma_f32_16x16x32_bf16 v[20:23], v[16:19], v[0:3], v[8:11]
	v_mfma_f32_16x16x32_bf16 v[8:11], v[12:15], v[4:7], 0
	v_mfma_f32_16x16x32_bf16 v[16:19], v[174:177], v[0:3], v[8:11]
	s_nop 4
	v_mfma_f32_16x16x32_bf16 v[8:11], v[152:155], v[4:7], 0
	v_mfma_f32_16x16x32_bf16 v[12:15], v[178:181], v[0:3], v[8:11]
	v_mfma_f32_16x16x32_bf16 v[8:11], v[170:173], v[4:7], 0
	v_mfma_f32_16x16x32_bf16 v[8:11], v[182:185], v[0:3], v[8:11]
	s_nop 4
	s_mov_b32 s30, 0xff800000
	v_max3_f32 v97, v68, s30, v69
	v_max3_f32 v97, v97, v70, v71
	v_max3_f32 v97, v97, v64, v65
	v_max3_f32 v97, v97, v66, v67
	v_max3_f32 v97, v97, v60, v61
	v_max3_f32 v97, v97, v62, v63
	v_max3_f32 v97, v97, v56, v57
	v_max3_f32 v97, v97, v58, v59
	v_max3_f32 v97, v97, v52, v53
	v_max3_f32 v97, v97, v54, v55
	v_max3_f32 v97, v97, v48, v49
	v_max3_f32 v97, v97, v50, v51
	v_max3_f32 v97, v97, v44, v45
	v_max3_f32 v97, v97, v46, v47
	v_max3_f32 v97, v97, v40, v41
	v_max3_f32 v97, v97, v42, v43
	v_max3_f32 v97, v97, v36, v37
	v_max3_f32 v97, v97, v38, v39
	v_max3_f32 v97, v97, v32, v33
	v_max3_f32 v97, v97, v34, v35
	v_max3_f32 v97, v97, v28, v29
	v_max3_f32 v97, v97, v30, v31
	v_max3_f32 v97, v97, v24, v25
	v_max3_f32 v97, v97, v26, v27
	v_max3_f32 v97, v97, v20, v21
	v_max3_f32 v97, v97, v22, v23
	v_max3_f32 v97, v97, v16, v17
	v_max3_f32 v97, v97, v18, v19
	v_max3_f32 v97, v97, v12, v13
	v_max3_f32 v97, v97, v14, v15
	v_max3_f32 v97, v97, v8, v9
	v_max3_f32 v97, v97, v10, v11
	v_mul_f32_e32 v97, 0x3e38aa3b, v97
	ds_bpermute_b32 v99, v114, v97
	ds_read_b128 v[152:155], v134 offset:32768
	ds_read_b128 v[170:173], v134 offset:40960
	ds_read_b128 v[174:177], v134 offset:49152
	ds_read_b128 v[178:181], v134 offset:57344
	ds_read_b128 v[182:185], v135 offset:32768
	ds_read_b128 v[186:189], v135 offset:40960
	ds_read_b128 v[190:193], v135 offset:49152
	ds_read_b128 v[194:197], v135 offset:57344
	s_waitcnt lgkmcnt(8)
	v_max_f32_e32 v99, v99, v99
	v_max_f32_e32 v97, v97, v99
	ds_bpermute_b32 v99, v115, v97
	s_waitcnt lgkmcnt(0)
; __device__ __forceinline__ unsigned cvt_pk_bf16(float lo, float hi) { const f32x2 v = (f32x2){lo, hi}; return __builtin_bit_cast(unsigned, __builtin_convertvector(v, bf16v2)); }
; #define AH_LDV(c, bufi) do { const int vaddr = vrow + (((vchunk0 + (c) * vcs + g) ^ qi) << 4); _Pragma("unroll") for (int dt = 0; dt < 4; ++dt) vf[bufi][dt] = *(const LAS bf16x8*)(lds + vaddr + dt * vpitch_dt); } while (0)
; template <bool LOC> ...
;     ...
;     const float alpha = __builtin_amdgcn_exp2f(mx - m2);
;     mx = m2; lsum *= alpha;
; #pragma unroll
;     for (int dt = 0; dt < 4; ++dt) o[dt] = o[dt] * alpha;
;     bf16x8 vf[2][4];
;     ...
;     AH_LDV(0, 0);
; #pragma unroll
;     for (int c = 0; c < 8; ++c) {
;         if (c < 7) AH_LDV(c + 1, (c + 1) & 1);
;         __builtin_amdgcn_sched_barrier(0);
;         float pe[8];
; #pragma unroll
;         for (int e = 0; e < 8; ++e) { pe[e] = __builtin_amdgcn_exp2f(s[c][e] - mx); lsum += pe[e]; }
;         u32x4 pw; pw.x = cvt_pk_bf16(pe[0], pe[1]); pw.y = cvt_pk_bf16(pe[2], pe[3]); pw.z = cvt_pk_bf16(pe[4], pe[5]); pw.w = cvt_pk_bf16(pe[6], pe[7]);
;         const bf16x8 pb = __builtin_bit_cast(bf16x8, pw);
; #pragma unroll
;         for (int dt = 0; dt < 4; ++dt) o[dt] = __builtin_amdgcn_mfma_f32_16x16x32_bf16(vf[c & 1][dt], pb, o[dt], 0, 0, 0);
;         __builtin_amdgcn_sched_barrier(0);
;     }
	v_max_f32_e32 v99, v99, v99
	v_max_f32_e32 v97, v97, v99
	v_sub_f32_e32 v99, 0xff800000, v97
	v_exp_f32_e32 v99, v99
	s_nop 0
	v_mul_f32_e32 v198, 0, v99
	v_mov_b32_e32 v199, v198
	v_mov_b32_e32 v200, v198
	v_mov_b32_e32 v201, v198
	v_mov_b32_e32 v206, v97
	v_mov_b32_e32 v207, v97
	v_mov_b32_e32 v208, s67
	v_mov_b32_e32 v209, s67
	v_mov_b32_e32 v210, 0
	v_mov_b32_e32 v211, 0
	v_pk_fma_f32 v[68:69], v[68:69], v[208:209], v[206:207] neg_lo:[0,0,1] neg_hi:[0,0,1]
	v_pk_fma_f32 v[70:71], v[70:71], v[208:209], v[206:207] neg_lo:[0,0,1] neg_hi:[0,0,1]
	v_exp_f32_e32 v68, v68
	v_pk_fma_f32 v[64:65], v[64:65], v[208:209], v[206:207] neg_lo:[0,0,1] neg_hi:[0,0,1]
	v_exp_f32_e32 v69, v69
	v_pk_fma_f32 v[66:67], v[66:67], v[208:209], v[206:207] neg_lo:[0,0,1] neg_hi:[0,0,1]
	v_exp_f32_e32 v70, v70
	v_exp_f32_e32 v71, v71
	v_exp_f32_e32 v212, v64
	v_pk_add_f32 v[210:211], v[210:211], v[68:69]
	v_exp_f32_e32 v213, v65
	v_pk_add_f32 v[210:211], v[210:211], v[70:71]
	v_exp_f32_e32 v214, v66
	v_exp_f32_e32 v215, v67
	v_pk_add_f32 v[210:211], v[210:211], v[212:213]
	v_cvt_pk_bf16_f32 v64, v68, v69
	v_pk_add_f32 v[210:211], v[210:211], v[214:215]
	v_cvt_pk_bf16_f32 v65, v70, v71
	v_cvt_pk_bf16_f32 v66, v212, v213
	v_cvt_pk_bf16_f32 v67, v214, v215
	s_nop 1
	v_mfma_f32_16x16x32_bf16 v[68:71], v[152:155], v[64:67], v[198:201]
	v_mfma_f32_16x16x32_bf16 v[152:155], v[170:173], v[64:67], v[198:201]
	v_mfma_f32_16x16x32_bf16 v[170:173], v[174:177], v[64:67], v[198:201]
	v_mfma_f32_16x16x32_bf16 v[64:67], v[178:181], v[64:67], v[198:201]
	ds_read_b128 v[174:177], v136 offset:32768
	ds_read_b128 v[178:181], v136 offset:40960
	s_nop 0
	ds_read_b128 v[198:201], v136 offset:49152
	ds_read_b128 v[202:205], v136 offset:57344
	v_pk_fma_f32 v[60:61], v[60:61], v[208:209], v[206:207] neg_lo:[0,0,1] neg_hi:[0,0,1]
	v_pk_fma_f32 v[62:63], v[62:63], v[208:209], v[206:207] neg_lo:[0,0,1] neg_hi:[0,0,1]
	v_exp_f32_e32 v60, v60
	v_pk_fma_f32 v[56:57], v[56:57], v[208:209], v[206:207] neg_lo:[0,0,1] neg_hi:[0,0,1]
	v_exp_f32_e32 v61, v61
	v_pk_fma_f32 v[58:59], v[58:59], v[208:209], v[206:207] neg_lo:[0,0,1] neg_hi:[0,0,1]
	v_exp_f32_e32 v62, v62
	v_exp_f32_e32 v63, v63
	v_exp_f32_e32 v212, v56
	v_pk_add_f32 v[210:211], v[210:211], v[60:61]
	v_exp_f32_e32 v213, v57
	v_pk_add_f32 v[210:211], v[210:211], v[62:63]
	v_exp_f32_e32 v214, v58
	v_exp_f32_e32 v215, v59
	v_pk_add_f32 v[210:211], v[210:211], v[212:213]
	v_cvt_pk_bf16_f32 v56, v60, v61
	v_pk_add_f32 v[210:211], v[210:211], v[214:215]
	v_cvt_pk_bf16_f32 v57, v62, v63
	v_cvt_pk_bf16_f32 v58, v212, v213
	v_cvt_pk_bf16_f32 v59, v214, v215
	s_nop 1
	v_mfma_f32_16x16x32_bf16 v[60:63], v[182:185], v[56:59], v[68:71]
	v_mfma_f32_16x16x32_bf16 v[68:71], v[186:189], v[56:59], v[152:155]
	v_mfma_f32_16x16x32_bf16 v[152:155], v[190:193], v[56:59], v[170:173]
	v_mfma_f32_16x16x32_bf16 v[56:59], v[194:197], v[56:59], v[64:67]
	s_nop 2
	ds_read_b128 v[64:67], v137 offset:32768
	ds_read_b128 v[170:173], v137 offset:40960
	ds_read_b128 v[182:185], v137 offset:49152
	ds_read_b128 v[186:189], v137 offset:57344
	v_pk_fma_f32 v[52:53], v[52:53], v[208:209], v[206:207] neg_lo:[0,0,1] neg_hi:[0,0,1]
	v_pk_fma_f32 v[54:55], v[54:55], v[208:209], v[206:207] neg_lo:[0,0,1] neg_hi:[0,0,1]
	v_exp_f32_e32 v52, v52
	v_pk_fma_f32 v[48:49], v[48:49], v[208:209], v[206:207] neg_lo:[0,0,1] neg_hi:[0,0,1]
	v_exp_f32_e32 v53, v53
	v_pk_fma_f32 v[50:51], v[50:51], v[208:209], v[206:207] neg_lo:[0,0,1] neg_hi:[0,0,1]
	v_exp_f32_e32 v54, v54
	v_exp_f32_e32 v55, v55
	v_exp_f32_e32 v212, v48
	v_pk_add_f32 v[210:211], v[210:211], v[52:53]
	v_exp_f32_e32 v213, v49
	v_pk_add_f32 v[210:211], v[210:211], v[54:55]
	v_exp_f32_e32 v214, v50
	v_exp_f32_e32 v215, v51
	v_pk_add_f32 v[210:211], v[210:211], v[212:213]
	v_cvt_pk_bf16_f32 v48, v52, v53
	v_pk_add_f32 v[210:211], v[210:211], v[214:215]
	v_cvt_pk_bf16_f32 v49, v54, v55
	v_cvt_pk_bf16_f32 v50, v212, v213
	v_cvt_pk_bf16_f32 v51, v214, v215
	s_waitcnt lgkmcnt(4)
	s_nop 0
	v_mfma_f32_16x16x32_bf16 v[52:55], v[174:177], v[48:51], v[60:63]
	v_mfma_f32_16x16x32_bf16 v[60:63], v[178:181], v[48:51], v[68:71]
	v_mfma_f32_16x16x32_bf16 v[68:71], v[198:201], v[48:51], v[152:155]
	v_mfma_f32_16x16x32_bf16 v[48:51], v[202:205], v[48:51], v[56:59]
	s_nop 2
	ds_read_b128 v[56:59], v138 offset:32768
	ds_read_b128 v[152:155], v138 offset:40960
	ds_read_b128 v[174:177], v138 offset:49152
	ds_read_b128 v[178:181], v138 offset:57344
	v_pk_fma_f32 v[44:45], v[44:45], v[208:209], v[206:207] neg_lo:[0,0,1] neg_hi:[0,0,1]
	v_pk_fma_f32 v[46:47], v[46:47], v[208:209], v[206:207] neg_lo:[0,0,1] neg_hi:[0,0,1]
	v_exp_f32_e32 v44, v44
	v_pk_fma_f32 v[40:41], v[40:41], v[208:209], v[206:207] neg_lo:[0,0,1] neg_hi:[0,0,1]
	v_exp_f32_e32 v45, v45
	v_pk_fma_f32 v[42:43], v[42:43], v[208:209], v[206:207] neg_lo:[0,0,1] neg_hi:[0,0,1]
	v_exp_f32_e32 v46, v46
	v_exp_f32_e32 v47, v47
	v_exp_f32_e32 v212, v40
	v_pk_add_f32 v[210:211], v[210:211], v[44:45]
	v_exp_f32_e32 v213, v41
	v_pk_add_f32 v[210:211], v[210:211], v[46:47]
	v_exp_f32_e32 v214, v42
	v_exp_f32_e32 v215, v43
	v_pk_add_f32 v[210:211], v[210:211], v[212:213]
	v_cvt_pk_bf16_f32 v40, v44, v45
	v_pk_add_f32 v[210:211], v[210:211], v[214:215]
	v_cvt_pk_bf16_f32 v41, v46, v47
	v_cvt_pk_bf16_f32 v42, v212, v213
	v_cvt_pk_bf16_f32 v43, v214, v215
	s_waitcnt lgkmcnt(4)
; __device__ __forceinline__ unsigned cvt_pk_bf16(float lo, float hi) { const f32x2 v = (f32x2){lo, hi}; return __builtin_bit_cast(unsigned, __builtin_convertvector(v, bf16v2)); }
; #define AH_LDV(c, bufi) do { const int vaddr = vrow + (((vchunk0 + (c) * vcs + g) ^ qi) << 4); _Pragma("unroll") for (int dt = 0; dt < 4; ++dt) vf[bufi][dt] = *(const LAS bf16x8*)(lds + vaddr + dt * vpitch_dt); } while (0)
; template <bool LOC> ...
;     ...
; #pragma unroll
;     for (int c = 0; c < 8; ++c) {
;         if (c < 7) AH_LDV(c + 1, (c + 1) & 1);
;         __builtin_amdgcn_sched_barrier(0);
;         float pe[8];
; #pragma unroll
;         for (int e = 0; e < 8; ++e) { pe[e] = __builtin_amdgcn_exp2f(s[c][e] - mx); lsum += pe[e]; }
;         u32x4 pw; pw.x = cvt_pk_bf16(pe[0], pe[1]); pw.y = cvt_pk_bf16(pe[2], pe[3]); pw.z = cvt_pk_bf16(pe[4], pe[5]); pw.w = cvt_pk_bf16(pe[6], pe[7]);
;         const bf16x8 pb = __builtin_bit_cast(bf16x8, pw);
; #pragma unroll
;         for (int dt = 0; dt < 4; ++dt) o[dt] = __builtin_amdgcn_mfma_f32_16x16x32_bf16(vf[c & 1][dt], pb, o[dt], 0, 0, 0);
;         __builtin_amdgcn_sched_barrier(0);
;     }
; __device__ __forceinline__ void phase_mixer(const Params& p, LAS unsigned char* lds, int l, bool with_ctx, int G, int tid, int wave, int lane, int rep_attn, int rep_pool) {
;     ...
;             for (int ps = 2 - npass; ps < 2; ++ps) {
;                 const int qtok = (ps == 1) ? (b * SEQ + r * 64 + 16 * n + qi) : (ML + b * CT + 16 * (sel * 8 + wave) + qi);
;                 const bf16_t* qp = PB + (size_t)qtok * PBW + 512 + h * 64 + 8 * g;
;                 qA0 = *(const bf16x8*)qp; qA1 = *(const bf16x8*)(qp + 32);
;                 mxA = -INFINITY; lA = 0.f;
; #pragma unroll
;                 for (int dt = 0; dt < 4; ++dt) oA[dt] = (f32x4){0.f, 0.f, 0.f, 0.f};
;                 attn_half<false>(lds, ka0, ka1, 32 * 128, vrow, 0, 4, 16 * 512, nullptr, 0, qA0, qA1, mxA, lA, oA, g, qi);
;                 if (ps == 0) attn_store(MIX, qtok, h, g, lA, oA);
	s_nop 0
	v_mfma_f32_16x16x32_bf16 v[44:47], v[64:67], v[40:43], v[52:55]
	v_mfma_f32_16x16x32_bf16 v[52:55], v[170:173], v[40:43], v[60:63]
	v_mfma_f32_16x16x32_bf16 v[60:63], v[182:185], v[40:43], v[68:71]
	v_mfma_f32_16x16x32_bf16 v[40:43], v[186:189], v[40:43], v[48:51]
	s_nop 2
	ds_read_b128 v[48:51], v139 offset:32768
	ds_read_b128 v[64:67], v139 offset:40960
	ds_read_b128 v[68:71], v139 offset:49152
	ds_read_b128 v[170:173], v139 offset:57344
	v_pk_fma_f32 v[36:37], v[36:37], v[208:209], v[206:207] neg_lo:[0,0,1] neg_hi:[0,0,1]
	v_pk_fma_f32 v[38:39], v[38:39], v[208:209], v[206:207] neg_lo:[0,0,1] neg_hi:[0,0,1]
	v_exp_f32_e32 v36, v36
	v_pk_fma_f32 v[32:33], v[32:33], v[208:209], v[206:207] neg_lo:[0,0,1] neg_hi:[0,0,1]
	v_exp_f32_e32 v37, v37
	v_pk_fma_f32 v[34:35], v[34:35], v[208:209], v[206:207] neg_lo:[0,0,1] neg_hi:[0,0,1]
	v_exp_f32_e32 v38, v38
	v_exp_f32_e32 v39, v39
	v_exp_f32_e32 v212, v32
	v_pk_add_f32 v[210:211], v[210:211], v[36:37]
	v_exp_f32_e32 v213, v33
	v_pk_add_f32 v[210:211], v[210:211], v[38:39]
	v_exp_f32_e32 v214, v34
	v_exp_f32_e32 v215, v35
	v_pk_add_f32 v[210:211], v[210:211], v[212:213]
	v_cvt_pk_bf16_f32 v32, v36, v37
	v_pk_add_f32 v[210:211], v[210:211], v[214:215]
	v_cvt_pk_bf16_f32 v33, v38, v39
	v_cvt_pk_bf16_f32 v34, v212, v213
	v_cvt_pk_bf16_f32 v35, v214, v215
	s_waitcnt lgkmcnt(4)
	s_nop 0
	v_mfma_f32_16x16x32_bf16 v[36:39], v[56:59], v[32:35], v[44:47]
	v_mfma_f32_16x16x32_bf16 v[44:47], v[152:155], v[32:35], v[52:55]
	v_mfma_f32_16x16x32_bf16 v[52:55], v[174:177], v[32:35], v[60:63]
	v_mfma_f32_16x16x32_bf16 v[32:35], v[178:181], v[32:35], v[40:43]
	s_nop 2
	ds_read_b128 v[40:43], v140 offset:32768
	ds_read_b128 v[56:59], v140 offset:40960
	ds_read_b128 v[60:63], v140 offset:49152
	ds_read_b128 v[152:155], v140 offset:57344
	v_pk_fma_f32 v[28:29], v[28:29], v[208:209], v[206:207] neg_lo:[0,0,1] neg_hi:[0,0,1]
	v_pk_fma_f32 v[30:31], v[30:31], v[208:209], v[206:207] neg_lo:[0,0,1] neg_hi:[0,0,1]
	v_exp_f32_e32 v28, v28
	v_pk_fma_f32 v[24:25], v[24:25], v[208:209], v[206:207] neg_lo:[0,0,1] neg_hi:[0,0,1]
	v_exp_f32_e32 v29, v29
	v_pk_fma_f32 v[26:27], v[26:27], v[208:209], v[206:207] neg_lo:[0,0,1] neg_hi:[0,0,1]
	v_exp_f32_e32 v30, v30
	v_exp_f32_e32 v31, v31
	v_exp_f32_e32 v212, v24
	v_pk_add_f32 v[210:211], v[210:211], v[28:29]
	v_exp_f32_e32 v213, v25
	v_pk_add_f32 v[210:211], v[210:211], v[30:31]
	v_exp_f32_e32 v214, v26
	v_exp_f32_e32 v215, v27
	v_pk_add_f32 v[210:211], v[210:211], v[212:213]
	v_cvt_pk_bf16_f32 v24, v28, v29
	v_pk_add_f32 v[210:211], v[210:211], v[214:215]
	v_cvt_pk_bf16_f32 v25, v30, v31
	v_cvt_pk_bf16_f32 v26, v212, v213
	v_cvt_pk_bf16_f32 v27, v214, v215
	s_waitcnt lgkmcnt(4)
	s_nop 0
	v_mfma_f32_16x16x32_bf16 v[28:31], v[48:51], v[24:27], v[36:39]
	v_mfma_f32_16x16x32_bf16 v[36:39], v[64:67], v[24:27], v[44:47]
	v_mfma_f32_16x16x32_bf16 v[44:47], v[68:71], v[24:27], v[52:55]
	v_mfma_f32_16x16x32_bf16 v[24:27], v[170:173], v[24:27], v[32:35]
	s_nop 2
	ds_read_b128 v[32:35], v141 offset:32768
	ds_read_b128 v[48:51], v141 offset:40960
	ds_read_b128 v[52:55], v141 offset:49152
	ds_read_b128 v[64:67], v141 offset:57344
	v_pk_fma_f32 v[20:21], v[20:21], v[208:209], v[206:207] neg_lo:[0,0,1] neg_hi:[0,0,1]
	v_pk_fma_f32 v[22:23], v[22:23], v[208:209], v[206:207] neg_lo:[0,0,1] neg_hi:[0,0,1]
	v_exp_f32_e32 v20, v20
	v_pk_fma_f32 v[16:17], v[16:17], v[208:209], v[206:207] neg_lo:[0,0,1] neg_hi:[0,0,1]
	v_exp_f32_e32 v21, v21
	v_pk_fma_f32 v[18:19], v[18:19], v[208:209], v[206:207] neg_lo:[0,0,1] neg_hi:[0,0,1]
	v_exp_f32_e32 v22, v22
	v_exp_f32_e32 v23, v23
	v_exp_f32_e32 v212, v16
	v_pk_add_f32 v[210:211], v[210:211], v[20:21]
	v_exp_f32_e32 v213, v17
	v_pk_add_f32 v[210:211], v[210:211], v[22:23]
	v_exp_f32_e32 v214, v18
	v_exp_f32_e32 v215, v19
	v_pk_add_f32 v[210:211], v[210:211], v[212:213]
	v_cvt_pk_bf16_f32 v16, v20, v21
	v_pk_add_f32 v[210:211], v[210:211], v[214:215]
	v_cvt_pk_bf16_f32 v17, v22, v23
	v_cvt_pk_bf16_f32 v18, v212, v213
	v_cvt_pk_bf16_f32 v19, v214, v215
	s_waitcnt lgkmcnt(4)
	s_nop 0
	v_mfma_f32_16x16x32_bf16 v[20:23], v[40:43], v[16:19], v[28:31]
	v_mfma_f32_16x16x32_bf16 v[36:39], v[56:59], v[16:19], v[36:39]
	v_mfma_f32_16x16x32_bf16 v[40:43], v[60:63], v[16:19], v[44:47]
	v_mfma_f32_16x16x32_bf16 v[24:27], v[152:155], v[16:19], v[24:27]
	v_pk_fma_f32 v[12:13], v[12:13], v[208:209], v[206:207] neg_lo:[0,0,1] neg_hi:[0,0,1]
	v_pk_fma_f32 v[14:15], v[14:15], v[208:209], v[206:207] neg_lo:[0,0,1] neg_hi:[0,0,1]
	v_exp_f32_e32 v12, v12
	v_pk_fma_f32 v[8:9], v[8:9], v[208:209], v[206:207] neg_lo:[0,0,1] neg_hi:[0,0,1]
	v_exp_f32_e32 v13, v13
	v_pk_fma_f32 v[10:11], v[10:11], v[208:209], v[206:207] neg_lo:[0,0,1] neg_hi:[0,0,1]
	v_exp_f32_e32 v14, v14
	v_exp_f32_e32 v15, v15
	v_exp_f32_e32 v212, v8
	v_pk_add_f32 v[210:211], v[210:211], v[12:13]
	v_exp_f32_e32 v213, v9
	v_pk_add_f32 v[210:211], v[210:211], v[14:15]
	v_exp_f32_e32 v214, v10
	v_exp_f32_e32 v215, v11
	v_pk_add_f32 v[210:211], v[210:211], v[212:213]
	v_cvt_pk_bf16_f32 v44, v12, v13
	v_pk_add_f32 v[210:211], v[210:211], v[214:215]
	v_cvt_pk_bf16_f32 v45, v14, v15
	v_cvt_pk_bf16_f32 v46, v212, v213
	v_cvt_pk_bf16_f32 v47, v214, v215
	v_add_f32_e32 v28, v210, v211
	s_waitcnt lgkmcnt(0)
	v_mfma_f32_16x16x32_bf16 v[8:11], v[32:35], v[44:47], v[20:23]
	v_mfma_f32_16x16x32_bf16 v[12:15], v[48:51], v[44:47], v[36:39]
	v_mfma_f32_16x16x32_bf16 v[16:19], v[52:55], v[44:47], v[40:43]
	v_mfma_f32_16x16x32_bf16 v[20:23], v[64:67], v[44:47], v[24:27]
	s_andn2_b64 vcc, exec, s[74:75]
	s_mov_b64 s[68:69], -1
	s_cbranch_vccnz .LBB0_298
; __device__ __forceinline__ unsigned cvt_pk_bf16(float lo, float hi) { const f32x2 v = (f32x2){lo, hi}; return __builtin_bit_cast(unsigned, __builtin_convertvector(v, bf16v2)); }
; __device__ __forceinline__ void attn_store(bf16_t* MIX, int qtok, int h, int g, float lsum, const f32x4 (&o)[4]) {
;     lsum += __shfl_xor(lsum, 16); lsum += __shfl_xor(lsum, 32);
;     const float inv = 1.f / lsum;
;     bf16_t* op = MIX + (size_t)qtok * DM + 512 + h * 64 + 4 * g;
; #pragma unroll
;     for (int dt = 0; dt < 4; ++dt) { u32x2 w; w.x = cvt_pk_bf16(o[dt][0] * inv, o[dt][1] * inv); w.y = cvt_pk_bf16(o[dt][2] * inv, o[dt][3] * inv); *(u32x2*)(op + 16 * dt) = w; }
; }
	ds_bpermute_b32 v24, v114, v28
	v_ashrrev_i32_e32 v105, 31, v104
	s_waitcnt lgkmcnt(0)
	v_add_f32_e32 v24, v28, v24
	ds_bpermute_b32 v25, v115, v24
	s_waitcnt lgkmcnt(0)
	v_add_f32_e32 v24, v24, v25
	v_div_scale_f32 v25, s[68:69], v24, v24, 1.0
	v_rcp_f32_e32 v26, v25
	s_mov_b64 s[68:69], 0
	v_fma_f32 v27, -v25, v26, 1.0
	v_fmac_f32_e32 v26, v27, v26
	v_div_scale_f32 v27, vcc, 1.0, v24, 1.0
	v_mul_f32_e32 v29, v27, v26
	v_fma_f32 v30, -v25, v29, v27
	v_fmac_f32_e32 v29, v30, v26
	v_fma_f32 v25, -v25, v29, v27
	v_div_fmas_f32 v25, v25, v26, v29
	v_div_fixup_f32 v24, v25, v24, 1.0
	v_lshlrev_b64 v[26:27], 11, v[104:105]
	v_pk_mul_f32 v[30:31], v[8:9], v[24:25] op_sel_hi:[1,0]
	v_pk_mul_f32 v[32:33], v[10:11], v[24:25] op_sel_hi:[1,0]
	v_lshl_add_u64 v[26:27], v[102:103], 0, v[26:27]
	v_cvt_pk_bf16_f32 v30, v30, v31
	v_cvt_pk_bf16_f32 v31, v32, v33
	global_store_dwordx2 v[26:27], v[30:31], off offset:1024
	v_pk_mul_f32 v[30:31], v[12:13], v[24:25] op_sel_hi:[1,0]
	v_pk_mul_f32 v[32:33], v[14:15], v[24:25] op_sel_hi:[1,0]
	v_cvt_pk_bf16_f32 v30, v30, v31
	v_cvt_pk_bf16_f32 v31, v32, v33
	global_store_dwordx2 v[26:27], v[30:31], off offset:1056
	v_pk_mul_f32 v[30:31], v[16:17], v[24:25] op_sel_hi:[1,0]
	v_pk_mul_f32 v[32:33], v[18:19], v[24:25] op_sel_hi:[1,0]
	v_cvt_pk_bf16_f32 v30, v30, v31
	v_cvt_pk_bf16_f32 v31, v32, v33
	global_store_dwordx2 v[26:27], v[30:31], off offset:1088
	v_pk_mul_f32 v[30:31], v[20:21], v[24:25] op_sel_hi:[1,0]
	v_pk_mul_f32 v[24:25], v[22:23], v[24:25] op_sel_hi:[1,0]
	v_cvt_pk_bf16_f32 v30, v30, v31
	v_cvt_pk_bf16_f32 v31, v24, v25
	global_store_dwordx2 v[26:27], v[30:31], off offset:1120
	s_branch .LBB0_298
